# 8-phase loops: first LDS-DMA piece of a phase issued before the fragment reads, second after (was both after)
# baseline (speedup 1.0000x reference)
; template <bool SWAP>
; DI void gemm_mainloop(f32x16 (&acc)[4][2], const u16* __restrict__ A, int lda, int rlo, int rhi,
;                       const u16* __restrict__ B, int ldb, int K, char* lds, const u16* zero_line) {
;     ...
;   auto glds = [&](int kt, int st) {
;     char* as_ = lds + st * 65536 + tid * 16;
; #pragma unroll
;     for (int i = 0; i < 4; ++i) {
;       const int rr = lr + 64 * i;
;       const u16* srca = (rr >= rlo && rr < rhi) ? (ap + (ptrdiff_t)(64 * i) * lda + kt * 64) : (zero_line + lc * 8);
;       __builtin_amdgcn_global_load_lds((const unsigned*)srca, (lds_u32*)(as_ + i * 8192), 16, 0, 0);
;       __builtin_amdgcn_global_load_lds((const unsigned*)(bp + (ptrdiff_t)(64 * i) * ldb + kt * 64), (lds_u32*)(as_ + 32768 + i * 8192), 16, 0, 0);
;     }
;   };
;     ...
; #pragma unroll 2
;   for (int kt = 0; kt < nk; ++kt) {
;     const char* st = lds + (kt & 1) * 65536;
;     ldfrag(st, 0, 0);
;     mma(1);
;     pat_rd();
;     if (kt + 1 < nk) glds(kt + 1, (kt + 1) & 1);
;     ldfrag(st, 1, 1);
;     mma(0);
;     pat_rd();
;     ldfrag(st, 2, 0);
;     mma(1);
;     pat_rd();
;     ldfrag(st, 3, 1);
;     mma(0);
;     pat_rd();
;     asm volatile("s_waitcnt vmcnt(0)" ::: "memory");
;     __syncthreads();
.Lg8_u0:
	s_add_u32 m0, s100, 0x14000
	s_mov_b64 exec, s[12:13]
	global_load_lds_dwordx4 v237, s[18:19]
	s_mov_b64 exec, -1
	v_add_u32_e32 v237, 0x80, v237
	v_add3_u32 v166, v249, v244, 0
	v_add3_u32 v167, v249, v245, 0
	v_add3_u32 v175, v249, v246, 0
	v_add3_u32 v185, v249, v247, 0
	ds_read_b128 v[176:179], v166 offset:32768
	ds_read_b128 v[180:183], v167 offset:32768
	ds_read_b128 v[186:189], v175 offset:32768
	ds_read_b128 v[190:193], v185 offset:32768
	v_add3_u32 v166, v248, v244, 0
	v_add3_u32 v167, v248, v245, 0
	v_add3_u32 v175, v248, v246, 0
	v_add3_u32 v185, v248, v247, 0
	ds_read_b128 v[130:133], v166
	ds_read_b128 v[134:137], v167
	ds_read_b128 v[138:141], v175
	ds_read_b128 v[142:145], v185
	ds_read_b128 v[146:149], v166 offset:4096
	ds_read_b128 v[150:153], v167 offset:4096
	ds_read_b128 v[158:161], v175 offset:4096
	ds_read_b128 v[162:165], v185 offset:4096
	s_add_u32 m0, s100, 0x16000
	s_mov_b64 exec, s[16:17]
	global_load_lds_dwordx4 v239, s[18:19]
	s_mov_b64 exec, -1
	v_add_u32_e32 v239, 0x80, v239
	s_waitcnt lgkmcnt(8)
	s_barrier
	s_waitcnt lgkmcnt(0)
	v_mfma_f32_32x32x16_bf16 v[114:129], v[176:179], v[130:133], v[114:129]
	v_mfma_f32_32x32x16_bf16 v[82:97], v[176:179], v[146:149], v[82:97]
	v_mfma_f32_32x32x16_bf16 v[114:129], v[180:183], v[134:137], v[114:129]
	v_mfma_f32_32x32x16_bf16 v[82:97], v[180:183], v[150:153], v[82:97]
	v_mfma_f32_32x32x16_bf16 v[114:129], v[186:189], v[138:141], v[114:129]
	v_mfma_f32_32x32x16_bf16 v[82:97], v[186:189], v[158:161], v[82:97]
	v_mfma_f32_32x32x16_bf16 v[114:129], v[190:193], v[142:145], v[114:129]
	v_mfma_f32_32x32x16_bf16 v[82:97], v[190:193], v[162:165], v[82:97]
	s_barrier
	s_add_u32 m0, s100, 0x8000
	s_nop 0
	global_load_lds_dwordx4 v240, s[22:23]
	v_add_u32_e32 v240, 0x80, v240
	v_add3_u32 v166, v249, v244, 0
	v_add3_u32 v167, v249, v245, 0
	v_add3_u32 v175, v249, v246, 0
	v_add3_u32 v185, v249, v247, 0
	ds_read_b128 v[194:197], v166 offset:49152
	ds_read_b128 v[198:201], v167 offset:49152
	ds_read_b128 v[228:231], v175 offset:49152
	ds_read_b128 v[232:235], v185 offset:49152
	s_add_u32 m0, s100, 0xa000
	s_nop 0
	global_load_lds_dwordx4 v242, s[22:23]
	v_add_u32_e32 v242, 0x80, v242
	s_barrier
	s_waitcnt lgkmcnt(0)
	v_mfma_f32_32x32x16_bf16 v[98:113], v[194:197], v[130:133], v[98:113]
	v_mfma_f32_32x32x16_bf16 v[66:81], v[194:197], v[146:149], v[66:81]
	v_mfma_f32_32x32x16_bf16 v[98:113], v[198:201], v[134:137], v[98:113]
	v_mfma_f32_32x32x16_bf16 v[66:81], v[198:201], v[150:153], v[66:81]
	v_mfma_f32_32x32x16_bf16 v[98:113], v[228:231], v[138:141], v[98:113]
	v_mfma_f32_32x32x16_bf16 v[66:81], v[228:231], v[158:161], v[66:81]
	v_mfma_f32_32x32x16_bf16 v[98:113], v[232:235], v[142:145], v[98:113]
	v_mfma_f32_32x32x16_bf16 v[66:81], v[232:235], v[162:165], v[66:81]
	s_barrier
	s_add_u32 m0, s100, 0x0
	s_mov_b64 exec, s[10:11]
	global_load_lds_dwordx4 v236, s[18:19]
	s_mov_b64 exec, -1
	v_add_u32_e32 v236, 0x80, v236
	v_add3_u32 v166, v248, v244, 0
	v_add3_u32 v167, v248, v245, 0
	v_add3_u32 v175, v248, v246, 0
	v_add3_u32 v185, v248, v247, 0
	ds_read_b128 v[130:133], v166 offset:16384
	ds_read_b128 v[134:137], v167 offset:16384
	ds_read_b128 v[138:141], v175 offset:16384
	ds_read_b128 v[142:145], v185 offset:16384
	ds_read_b128 v[146:149], v166 offset:20480
	ds_read_b128 v[150:153], v167 offset:20480
	ds_read_b128 v[158:161], v175 offset:20480
	ds_read_b128 v[162:165], v185 offset:20480
	s_add_u32 m0, s100, 0x2000
	s_mov_b64 exec, s[14:15]
	global_load_lds_dwordx4 v238, s[18:19]
	s_mov_b64 exec, -1
	v_add_u32_e32 v238, 0x80, v238
	s_barrier
	s_waitcnt lgkmcnt(0)
	v_mfma_f32_32x32x16_bf16 v[50:65], v[176:179], v[130:133], v[50:65]
	v_mfma_f32_32x32x16_bf16 v[18:33], v[176:179], v[146:149], v[18:33]
	v_mfma_f32_32x32x16_bf16 v[50:65], v[180:183], v[134:137], v[50:65]
	v_mfma_f32_32x32x16_bf16 v[18:33], v[180:183], v[150:153], v[18:33]
	v_mfma_f32_32x32x16_bf16 v[50:65], v[186:189], v[138:141], v[50:65]
	v_mfma_f32_32x32x16_bf16 v[18:33], v[186:189], v[158:161], v[18:33]
	v_mfma_f32_32x32x16_bf16 v[50:65], v[190:193], v[142:145], v[50:65]
	v_mfma_f32_32x32x16_bf16 v[18:33], v[190:193], v[162:165], v[18:33]
	s_barrier
	s_add_u32 m0, s100, 0xc000
	s_nop 0
	global_load_lds_dwordx4 v241, s[22:23]
	v_add_u32_e32 v241, 0x80, v241
	s_add_u32 m0, s100, 0xe000
	s_nop 0
	global_load_lds_dwordx4 v243, s[22:23]
	v_add_u32_e32 v243, 0x80, v243
	s_waitcnt vmcnt(6)
	s_barrier
	v_mfma_f32_32x32x16_bf16 v[34:49], v[194:197], v[130:133], v[34:49]
	v_mfma_f32_32x32x16_bf16 v[2:17], v[194:197], v[146:149], v[2:17]
	v_mfma_f32_32x32x16_bf16 v[34:49], v[198:201], v[134:137], v[34:49]
	v_mfma_f32_32x32x16_bf16 v[2:17], v[198:201], v[150:153], v[2:17]
	v_mfma_f32_32x32x16_bf16 v[34:49], v[228:231], v[138:141], v[34:49]
	v_mfma_f32_32x32x16_bf16 v[2:17], v[228:231], v[158:161], v[2:17]
	v_mfma_f32_32x32x16_bf16 v[34:49], v[232:235], v[142:145], v[34:49]
	v_mfma_f32_32x32x16_bf16 v[2:17], v[232:235], v[162:165], v[2:17]
	s_barrier
	s_add_u32 m0, s100, 0x4000
	s_mov_b64 exec, s[12:13]
	global_load_lds_dwordx4 v237, s[18:19]
	s_mov_b64 exec, -1
	v_add_u32_e32 v237, 0x80, v237
	v_add3_u32 v166, v249, v244, s21
	v_add3_u32 v167, v249, v245, s21
	v_add3_u32 v175, v249, v246, s21
	v_add3_u32 v185, v249, v247, s21
	ds_read_b128 v[176:179], v166 offset:32768
	ds_read_b128 v[180:183], v167 offset:32768
	ds_read_b128 v[186:189], v175 offset:32768
	ds_read_b128 v[190:193], v185 offset:32768
	v_add3_u32 v166, v248, v244, s21
	v_add3_u32 v167, v248, v245, s21
	v_add3_u32 v175, v248, v246, s21
	v_add3_u32 v185, v248, v247, s21
	ds_read_b128 v[130:133], v166
	ds_read_b128 v[134:137], v167
	ds_read_b128 v[138:141], v175
	ds_read_b128 v[142:145], v185
	ds_read_b128 v[146:149], v166 offset:4096
	ds_read_b128 v[150:153], v167 offset:4096
	ds_read_b128 v[158:161], v175 offset:4096
	ds_read_b128 v[162:165], v185 offset:4096
	s_add_u32 m0, s100, 0x6000
	s_mov_b64 exec, s[16:17]
	global_load_lds_dwordx4 v239, s[18:19]
	s_mov_b64 exec, -1
	v_add_u32_e32 v239, 0x80, v239
	s_waitcnt lgkmcnt(8)
	s_barrier
; template <bool SWAP>
; DI void gemm_mainloop(f32x16 (&acc)[4][2], const u16* __restrict__ A, int lda, int rlo, int rhi,
;                       const u16* __restrict__ B, int ldb, int K, char* lds, const u16* zero_line) {
;     ...
; #pragma unroll 2
;   for (int kt = 0; kt < nk; ++kt) {
;     const char* st = lds + (kt & 1) * 65536;
;     ldfrag(st, 0, 0);
;     mma(1);
;     pat_rd();
;     if (kt + 1 < nk) glds(kt + 1, (kt + 1) & 1);
;     ldfrag(st, 1, 1);
;     mma(0);
;     pat_rd();
;     ldfrag(st, 2, 0);
;     mma(1);
;     pat_rd();
;     ldfrag(st, 3, 1);
;     mma(0);
;     pat_rd();
;     asm volatile("s_waitcnt vmcnt(0)" ::: "memory");
;     __syncthreads();
;   }
	s_waitcnt lgkmcnt(0)
	v_mfma_f32_32x32x16_bf16 v[114:129], v[176:179], v[130:133], v[114:129]
	v_mfma_f32_32x32x16_bf16 v[82:97], v[176:179], v[146:149], v[82:97]
	v_mfma_f32_32x32x16_bf16 v[114:129], v[180:183], v[134:137], v[114:129]
	v_mfma_f32_32x32x16_bf16 v[82:97], v[180:183], v[150:153], v[82:97]
	v_mfma_f32_32x32x16_bf16 v[114:129], v[186:189], v[138:141], v[114:129]
	v_mfma_f32_32x32x16_bf16 v[82:97], v[186:189], v[158:161], v[82:97]
	v_mfma_f32_32x32x16_bf16 v[114:129], v[190:193], v[142:145], v[114:129]
	v_mfma_f32_32x32x16_bf16 v[82:97], v[190:193], v[162:165], v[82:97]
	s_barrier
	s_add_u32 m0, s100, 0x18000
	s_nop 0
	global_load_lds_dwordx4 v240, s[22:23]
	v_add_u32_e32 v240, 0x80, v240
	v_add3_u32 v166, v249, v244, s21
	v_add3_u32 v167, v249, v245, s21
	v_add3_u32 v175, v249, v246, s21
	v_add3_u32 v185, v249, v247, s21
	ds_read_b128 v[194:197], v166 offset:49152
	ds_read_b128 v[198:201], v167 offset:49152
	ds_read_b128 v[228:231], v175 offset:49152
	ds_read_b128 v[232:235], v185 offset:49152
	s_add_u32 m0, s100, 0x1a000
	s_nop 0
	global_load_lds_dwordx4 v242, s[22:23]
	v_add_u32_e32 v242, 0x80, v242
	s_barrier
	s_waitcnt lgkmcnt(0)
	v_mfma_f32_32x32x16_bf16 v[98:113], v[194:197], v[130:133], v[98:113]
	v_mfma_f32_32x32x16_bf16 v[66:81], v[194:197], v[146:149], v[66:81]
	v_mfma_f32_32x32x16_bf16 v[98:113], v[198:201], v[134:137], v[98:113]
	v_mfma_f32_32x32x16_bf16 v[66:81], v[198:201], v[150:153], v[66:81]
	v_mfma_f32_32x32x16_bf16 v[98:113], v[228:231], v[138:141], v[98:113]
	v_mfma_f32_32x32x16_bf16 v[66:81], v[228:231], v[158:161], v[66:81]
	v_mfma_f32_32x32x16_bf16 v[98:113], v[232:235], v[142:145], v[98:113]
	v_mfma_f32_32x32x16_bf16 v[66:81], v[232:235], v[162:165], v[66:81]
	s_barrier
	s_add_u32 m0, s100, 0x10000
	s_mov_b64 exec, s[10:11]
	global_load_lds_dwordx4 v236, s[18:19]
	s_mov_b64 exec, -1
	v_add_u32_e32 v236, 0x80, v236
	v_add3_u32 v166, v248, v244, s21
	v_add3_u32 v167, v248, v245, s21
	v_add3_u32 v175, v248, v246, s21
	v_add3_u32 v185, v248, v247, s21
	ds_read_b128 v[130:133], v166 offset:16384
	ds_read_b128 v[134:137], v167 offset:16384
	ds_read_b128 v[138:141], v175 offset:16384
	ds_read_b128 v[142:145], v185 offset:16384
	ds_read_b128 v[146:149], v166 offset:20480
	ds_read_b128 v[150:153], v167 offset:20480
	ds_read_b128 v[158:161], v175 offset:20480
	ds_read_b128 v[162:165], v185 offset:20480
	s_add_u32 m0, s100, 0x12000
	s_mov_b64 exec, s[14:15]
	global_load_lds_dwordx4 v238, s[18:19]
	s_mov_b64 exec, -1
	v_add_u32_e32 v238, 0x80, v238
	s_barrier
	s_waitcnt lgkmcnt(0)
	v_mfma_f32_32x32x16_bf16 v[50:65], v[176:179], v[130:133], v[50:65]
	v_mfma_f32_32x32x16_bf16 v[18:33], v[176:179], v[146:149], v[18:33]
	v_mfma_f32_32x32x16_bf16 v[50:65], v[180:183], v[134:137], v[50:65]
	v_mfma_f32_32x32x16_bf16 v[18:33], v[180:183], v[150:153], v[18:33]
	v_mfma_f32_32x32x16_bf16 v[50:65], v[186:189], v[138:141], v[50:65]
	v_mfma_f32_32x32x16_bf16 v[18:33], v[186:189], v[158:161], v[18:33]
	v_mfma_f32_32x32x16_bf16 v[50:65], v[190:193], v[142:145], v[50:65]
	v_mfma_f32_32x32x16_bf16 v[18:33], v[190:193], v[162:165], v[18:33]
	s_barrier
	s_add_u32 m0, s100, 0x1c000
	s_nop 0
	global_load_lds_dwordx4 v241, s[22:23]
	v_add_u32_e32 v241, 0x80, v241
	s_add_u32 m0, s100, 0x1e000
	s_nop 0
	global_load_lds_dwordx4 v243, s[22:23]
	v_add_u32_e32 v243, 0x80, v243
	s_waitcnt vmcnt(6)
	s_barrier
	v_mfma_f32_32x32x16_bf16 v[34:49], v[194:197], v[130:133], v[34:49]
	v_mfma_f32_32x32x16_bf16 v[2:17], v[194:197], v[146:149], v[2:17]
	v_mfma_f32_32x32x16_bf16 v[34:49], v[198:201], v[134:137], v[34:49]
	v_mfma_f32_32x32x16_bf16 v[2:17], v[198:201], v[150:153], v[2:17]
	v_mfma_f32_32x32x16_bf16 v[34:49], v[228:231], v[138:141], v[34:49]
	v_mfma_f32_32x32x16_bf16 v[2:17], v[228:231], v[158:161], v[2:17]
	v_mfma_f32_32x32x16_bf16 v[34:49], v[232:235], v[142:145], v[34:49]
	v_mfma_f32_32x32x16_bf16 v[2:17], v[232:235], v[162:165], v[2:17]
	s_barrier
	s_add_i32 s29, s29, 2
	s_cmp_lt_u32 s29, 14
	s_cbranch_scc1 .Lg8_u0
	v_add3_u32 v166, v249, v244, 0
	v_add3_u32 v167, v249, v245, 0
	v_add3_u32 v175, v249, v246, 0
	v_add3_u32 v185, v249, v247, 0
	ds_read_b128 v[176:179], v166 offset:32768
	ds_read_b128 v[180:183], v167 offset:32768
	ds_read_b128 v[186:189], v175 offset:32768
	ds_read_b128 v[190:193], v185 offset:32768
	v_add3_u32 v166, v248, v244, 0
	v_add3_u32 v167, v248, v245, 0
	v_add3_u32 v175, v248, v246, 0
	v_add3_u32 v185, v248, v247, 0
	ds_read_b128 v[130:133], v166
	ds_read_b128 v[134:137], v167
	ds_read_b128 v[138:141], v175
	ds_read_b128 v[142:145], v185
	ds_read_b128 v[146:149], v166 offset:4096
	ds_read_b128 v[150:153], v167 offset:4096
	ds_read_b128 v[158:161], v175 offset:4096
	ds_read_b128 v[162:165], v185 offset:4096
	s_add_u32 m0, s100, 0x14000
	s_mov_b64 exec, s[12:13]
	global_load_lds_dwordx4 v237, s[18:19]
	s_mov_b64 exec, -1
	v_add_u32_e32 v237, 0x80, v237
	s_add_u32 m0, s100, 0x16000
	s_mov_b64 exec, s[16:17]
	global_load_lds_dwordx4 v239, s[18:19]
	s_mov_b64 exec, -1
	v_add_u32_e32 v239, 0x80, v239
	s_barrier
	s_waitcnt lgkmcnt(0)
	v_mfma_f32_32x32x16_bf16 v[114:129], v[176:179], v[130:133], v[114:129]
	v_mfma_f32_32x32x16_bf16 v[82:97], v[176:179], v[146:149], v[82:97]
	v_mfma_f32_32x32x16_bf16 v[114:129], v[180:183], v[134:137], v[114:129]
	v_mfma_f32_32x32x16_bf16 v[82:97], v[180:183], v[150:153], v[82:97]
	v_mfma_f32_32x32x16_bf16 v[114:129], v[186:189], v[138:141], v[114:129]
	v_mfma_f32_32x32x16_bf16 v[82:97], v[186:189], v[158:161], v[82:97]
	v_mfma_f32_32x32x16_bf16 v[114:129], v[190:193], v[142:145], v[114:129]
	v_mfma_f32_32x32x16_bf16 v[82:97], v[190:193], v[162:165], v[82:97]
	s_barrier
; template <bool SWAP>
; DI void gemm_mainloop(f32x16 (&acc)[4][2], const u16* __restrict__ A, int lda, int rlo, int rhi,
;                       const u16* __restrict__ B, int ldb, int K, char* lds, const u16* zero_line) {
;     ...
; #pragma unroll 2
;   for (int kt = 0; kt < nk; ++kt) {
;     const char* st = lds + (kt & 1) * 65536;
;     ldfrag(st, 0, 0);
;     mma(1);
;     pat_rd();
;     if (kt + 1 < nk) glds(kt + 1, (kt + 1) & 1);
;     ldfrag(st, 1, 1);
;     mma(0);
;     pat_rd();
;     ldfrag(st, 2, 0);
;     mma(1);
;     pat_rd();
;     ldfrag(st, 3, 1);
;     mma(0);
;     pat_rd();
;     asm volatile("s_waitcnt vmcnt(0)" ::: "memory");
;     __syncthreads();
;   }
;   mma(1);
	v_add3_u32 v166, v249, v244, 0
	v_add3_u32 v167, v249, v245, 0
	v_add3_u32 v175, v249, v246, 0
	v_add3_u32 v185, v249, v247, 0
	ds_read_b128 v[194:197], v166 offset:49152
	ds_read_b128 v[198:201], v167 offset:49152
	ds_read_b128 v[228:231], v175 offset:49152
	ds_read_b128 v[232:235], v185 offset:49152
	s_barrier
	s_waitcnt lgkmcnt(0)
	v_mfma_f32_32x32x16_bf16 v[98:113], v[194:197], v[130:133], v[98:113]
	v_mfma_f32_32x32x16_bf16 v[66:81], v[194:197], v[146:149], v[66:81]
	v_mfma_f32_32x32x16_bf16 v[98:113], v[198:201], v[134:137], v[98:113]
	v_mfma_f32_32x32x16_bf16 v[66:81], v[198:201], v[150:153], v[66:81]
	v_mfma_f32_32x32x16_bf16 v[98:113], v[228:231], v[138:141], v[98:113]
	v_mfma_f32_32x32x16_bf16 v[66:81], v[228:231], v[158:161], v[66:81]
	v_mfma_f32_32x32x16_bf16 v[98:113], v[232:235], v[142:145], v[98:113]
	v_mfma_f32_32x32x16_bf16 v[66:81], v[232:235], v[162:165], v[66:81]
	s_barrier
	v_add3_u32 v166, v248, v244, 0
	v_add3_u32 v167, v248, v245, 0
	v_add3_u32 v175, v248, v246, 0
	v_add3_u32 v185, v248, v247, 0
	ds_read_b128 v[130:133], v166 offset:16384
	ds_read_b128 v[134:137], v167 offset:16384
	ds_read_b128 v[138:141], v175 offset:16384
	ds_read_b128 v[142:145], v185 offset:16384
	ds_read_b128 v[146:149], v166 offset:20480
	ds_read_b128 v[150:153], v167 offset:20480
	ds_read_b128 v[158:161], v175 offset:20480
	ds_read_b128 v[162:165], v185 offset:20480
	s_waitcnt vmcnt(4)
	s_barrier
	s_waitcnt lgkmcnt(0)
	v_mfma_f32_32x32x16_bf16 v[50:65], v[176:179], v[130:133], v[50:65]
	v_mfma_f32_32x32x16_bf16 v[18:33], v[176:179], v[146:149], v[18:33]
	v_mfma_f32_32x32x16_bf16 v[50:65], v[180:183], v[134:137], v[50:65]
	v_mfma_f32_32x32x16_bf16 v[18:33], v[180:183], v[150:153], v[18:33]
	v_mfma_f32_32x32x16_bf16 v[50:65], v[186:189], v[138:141], v[50:65]
	v_mfma_f32_32x32x16_bf16 v[18:33], v[186:189], v[158:161], v[18:33]
	v_mfma_f32_32x32x16_bf16 v[50:65], v[190:193], v[142:145], v[50:65]
	v_mfma_f32_32x32x16_bf16 v[18:33], v[190:193], v[162:165], v[18:33]
	v_mfma_f32_32x32x16_bf16 v[34:49], v[194:197], v[130:133], v[34:49]
	v_mfma_f32_32x32x16_bf16 v[2:17], v[194:197], v[146:149], v[2:17]
	v_mfma_f32_32x32x16_bf16 v[34:49], v[198:201], v[134:137], v[34:49]
	v_mfma_f32_32x32x16_bf16 v[2:17], v[198:201], v[150:153], v[2:17]
	v_mfma_f32_32x32x16_bf16 v[34:49], v[228:231], v[138:141], v[34:49]
	v_mfma_f32_32x32x16_bf16 v[2:17], v[228:231], v[158:161], v[2:17]
	v_mfma_f32_32x32x16_bf16 v[34:49], v[232:235], v[142:145], v[34:49]
	v_mfma_f32_32x32x16_bf16 v[2:17], v[232:235], v[162:165], v[2:17]
	s_barrier
	v_add3_u32 v166, v249, v244, s21
	v_add3_u32 v167, v249, v245, s21
	v_add3_u32 v175, v249, v246, s21
	v_add3_u32 v185, v249, v247, s21
	ds_read_b128 v[176:179], v166 offset:32768
	ds_read_b128 v[180:183], v167 offset:32768
	ds_read_b128 v[186:189], v175 offset:32768
	ds_read_b128 v[190:193], v185 offset:32768
	v_add3_u32 v166, v248, v244, s21
	v_add3_u32 v167, v248, v245, s21
	v_add3_u32 v175, v248, v246, s21
	v_add3_u32 v185, v248, v247, s21
	ds_read_b128 v[130:133], v166
	ds_read_b128 v[134:137], v167
	ds_read_b128 v[138:141], v175
	ds_read_b128 v[142:145], v185
	ds_read_b128 v[146:149], v166 offset:4096
	ds_read_b128 v[150:153], v167 offset:4096
	ds_read_b128 v[158:161], v175 offset:4096
	ds_read_b128 v[162:165], v185 offset:4096
	s_waitcnt vmcnt(2)
	s_barrier
	s_waitcnt lgkmcnt(0)
	v_mfma_f32_32x32x16_bf16 v[114:129], v[176:179], v[130:133], v[114:129]
	v_mfma_f32_32x32x16_bf16 v[82:97], v[176:179], v[146:149], v[82:97]
	v_mfma_f32_32x32x16_bf16 v[114:129], v[180:183], v[134:137], v[114:129]
	v_mfma_f32_32x32x16_bf16 v[82:97], v[180:183], v[150:153], v[82:97]
	v_mfma_f32_32x32x16_bf16 v[114:129], v[186:189], v[138:141], v[114:129]
	v_mfma_f32_32x32x16_bf16 v[82:97], v[186:189], v[158:161], v[82:97]
	v_mfma_f32_32x32x16_bf16 v[114:129], v[190:193], v[142:145], v[114:129]
	v_mfma_f32_32x32x16_bf16 v[82:97], v[190:193], v[162:165], v[82:97]
	s_barrier
	v_add3_u32 v166, v249, v244, s21
	v_add3_u32 v167, v249, v245, s21
	v_add3_u32 v175, v249, v246, s21
	v_add3_u32 v185, v249, v247, s21
	ds_read_b128 v[194:197], v166 offset:49152
	ds_read_b128 v[198:201], v167 offset:49152
	ds_read_b128 v[228:231], v175 offset:49152
	ds_read_b128 v[232:235], v185 offset:49152
	s_waitcnt vmcnt(0)
	s_barrier
	s_waitcnt lgkmcnt(0)
	v_mfma_f32_32x32x16_bf16 v[98:113], v[194:197], v[130:133], v[98:113]
	v_mfma_f32_32x32x16_bf16 v[66:81], v[194:197], v[146:149], v[66:81]
	v_mfma_f32_32x32x16_bf16 v[98:113], v[198:201], v[134:137], v[98:113]
	v_mfma_f32_32x32x16_bf16 v[66:81], v[198:201], v[150:153], v[66:81]
	v_mfma_f32_32x32x16_bf16 v[98:113], v[228:231], v[138:141], v[98:113]
	v_mfma_f32_32x32x16_bf16 v[66:81], v[228:231], v[158:161], v[66:81]
	v_mfma_f32_32x32x16_bf16 v[98:113], v[232:235], v[142:145], v[98:113]
	v_mfma_f32_32x32x16_bf16 v[66:81], v[232:235], v[162:165], v[66:81]
	s_barrier
	v_add3_u32 v166, v248, v244, s21
	v_add3_u32 v167, v248, v245, s21
	v_add3_u32 v175, v248, v246, s21
	v_add3_u32 v185, v248, v247, s21
	ds_read_b128 v[130:133], v166 offset:16384
	ds_read_b128 v[134:137], v167 offset:16384
	ds_read_b128 v[138:141], v175 offset:16384
	ds_read_b128 v[142:145], v185 offset:16384
	ds_read_b128 v[146:149], v166 offset:20480
	ds_read_b128 v[150:153], v167 offset:20480
	ds_read_b128 v[158:161], v175 offset:20480
	ds_read_b128 v[162:165], v185 offset:20480
	s_barrier
	s_waitcnt lgkmcnt(0)
	v_mfma_f32_32x32x16_bf16 v[50:65], v[176:179], v[130:133], v[50:65]
	v_mfma_f32_32x32x16_bf16 v[18:33], v[176:179], v[146:149], v[18:33]
	v_mfma_f32_32x32x16_bf16 v[50:65], v[180:183], v[134:137], v[50:65]
	v_mfma_f32_32x32x16_bf16 v[18:33], v[180:183], v[150:153], v[18:33]
	v_mfma_f32_32x32x16_bf16 v[50:65], v[186:189], v[138:141], v[50:65]
	v_mfma_f32_32x32x16_bf16 v[18:33], v[186:189], v[158:161], v[18:33]
	v_mfma_f32_32x32x16_bf16 v[50:65], v[190:193], v[142:145], v[50:65]
	v_mfma_f32_32x32x16_bf16 v[18:33], v[190:193], v[162:165], v[18:33]
	v_mfma_f32_32x32x16_bf16 v[34:49], v[194:197], v[130:133], v[34:49]
	v_mfma_f32_32x32x16_bf16 v[2:17], v[194:197], v[146:149], v[2:17]
	v_mfma_f32_32x32x16_bf16 v[34:49], v[198:201], v[134:137], v[34:49]
	v_mfma_f32_32x32x16_bf16 v[2:17], v[198:201], v[150:153], v[2:17]
	v_mfma_f32_32x32x16_bf16 v[34:49], v[228:231], v[138:141], v[34:49]
	v_mfma_f32_32x32x16_bf16 v[2:17], v[228:231], v[158:161], v[2:17]
	v_mfma_f32_32x32x16_bf16 v[34:49], v[232:235], v[142:145], v[34:49]
	v_mfma_f32_32x32x16_bf16 v[2:17], v[232:235], v[162:165], v[2:17]
	s_barrier
	s_cmp_eq_u32 s101, 0
	s_cbranch_scc0 .Lg8_u0_p1
	s_barrier

; template <bool SWAP>
; DI void gemm_mainloop(f32x16 (&acc)[4][2], const u16* __restrict__ A, int lda, int rlo, int rhi,
;                       const u16* __restrict__ B, int ldb, int K, char* lds, const u16* zero_line) {
;     ...
;   auto glds = [&](int kt, int st) {
;     char* as_ = lds + st * 65536 + tid * 16;
; #pragma unroll
;     for (int i = 0; i < 4; ++i) {
;       const int rr = lr + 64 * i;
;       const u16* srca = (rr >= rlo && rr < rhi) ? (ap + (ptrdiff_t)(64 * i) * lda + kt * 64) : (zero_line + lc * 8);
;       __builtin_amdgcn_global_load_lds((const unsigned*)srca, (lds_u32*)(as_ + i * 8192), 16, 0, 0);
;       __builtin_amdgcn_global_load_lds((const unsigned*)(bp + (ptrdiff_t)(64 * i) * ldb + kt * 64), (lds_u32*)(as_ + 32768 + i * 8192), 16, 0, 0);
;     }
;   };
;     ...
; #pragma unroll 2
;   for (int kt = 0; kt < nk; ++kt) {
;     const char* st = lds + (kt & 1) * 65536;
;     ldfrag(st, 0, 0);
;     mma(1);
;     pat_rd();
;     if (kt + 1 < nk) glds(kt + 1, (kt + 1) & 1);
;     ldfrag(st, 1, 1);
;     mma(0);
;     pat_rd();
;     ldfrag(st, 2, 0);
;     mma(1);
;     pat_rd();
;     ldfrag(st, 3, 1);
;     mma(0);
;     pat_rd();
;     asm volatile("s_waitcnt vmcnt(0)" ::: "memory");
;     __syncthreads();
.Lg8_qa:
	s_add_u32 m0, s100, 0x14000
	s_nop 0
	global_load_lds_dwordx4 v233, s[6:7]
	v_add_u32_e32 v233, 0x80, v233
	v_add3_u32 v246, v245, v240, 0
	v_add3_u32 v247, v245, v241, 0
	v_add3_u32 v248, v245, v242, 0
	v_add3_u32 v249, v245, v243, 0
	ds_read_b128 v[170:173], v246 offset:32768
	ds_read_b128 v[174:177], v247 offset:32768
	ds_read_b128 v[178:181], v248 offset:32768
	ds_read_b128 v[186:189], v249 offset:32768
	v_add3_u32 v246, v244, v240, 0
	v_add3_u32 v247, v244, v241, 0
	v_add3_u32 v248, v244, v242, 0
	v_add3_u32 v249, v244, v243, 0
	ds_read_b128 v[130:133], v246
	ds_read_b128 v[134:137], v247
	ds_read_b128 v[138:141], v248
	ds_read_b128 v[142:145], v249
	ds_read_b128 v[146:149], v246 offset:4096
	ds_read_b128 v[150:153], v247 offset:4096
	ds_read_b128 v[156:159], v248 offset:4096
	ds_read_b128 v[160:163], v249 offset:4096
	s_add_u32 m0, s100, 0x16000
	s_nop 0
	global_load_lds_dwordx4 v235, s[6:7]
	v_add_u32_e32 v235, 0x80, v235
	s_waitcnt lgkmcnt(8)
	s_barrier
	s_waitcnt lgkmcnt(0)
	v_mfma_f32_32x32x16_bf16 v[114:129], v[130:133], v[170:173], v[114:129]
	v_mfma_f32_32x32x16_bf16 v[82:97], v[146:149], v[170:173], v[82:97]
	v_mfma_f32_32x32x16_bf16 v[114:129], v[134:137], v[174:177], v[114:129]
	v_mfma_f32_32x32x16_bf16 v[82:97], v[150:153], v[174:177], v[82:97]
	v_mfma_f32_32x32x16_bf16 v[114:129], v[138:141], v[178:181], v[114:129]
	v_mfma_f32_32x32x16_bf16 v[82:97], v[156:159], v[178:181], v[82:97]
	v_mfma_f32_32x32x16_bf16 v[114:129], v[142:145], v[186:189], v[114:129]
	v_mfma_f32_32x32x16_bf16 v[82:97], v[160:163], v[186:189], v[82:97]
	s_barrier
	s_add_u32 m0, s100, 0x8000
	s_nop 0
	global_load_lds_dwordx4 v236, s[8:9]
	v_add_u32_e32 v236, 0x80, v236
	v_add3_u32 v246, v245, v240, 0
	v_add3_u32 v247, v245, v241, 0
	v_add3_u32 v248, v245, v242, 0
	v_add3_u32 v249, v245, v243, 0
	ds_read_b128 v[190:193], v246 offset:49152
	ds_read_b128 v[194:197], v247 offset:49152
	ds_read_b128 v[198:201], v248 offset:49152
	ds_read_b128 v[228:231], v249 offset:49152
	s_add_u32 m0, s100, 0xa000
	s_nop 0
	global_load_lds_dwordx4 v238, s[8:9]
	v_add_u32_e32 v238, 0x80, v238
	s_barrier
	s_waitcnt lgkmcnt(0)
	v_mfma_f32_32x32x16_bf16 v[98:113], v[130:133], v[190:193], v[98:113]
	v_mfma_f32_32x32x16_bf16 v[66:81], v[146:149], v[190:193], v[66:81]
	v_mfma_f32_32x32x16_bf16 v[98:113], v[134:137], v[194:197], v[98:113]
	v_mfma_f32_32x32x16_bf16 v[66:81], v[150:153], v[194:197], v[66:81]
	v_mfma_f32_32x32x16_bf16 v[98:113], v[138:141], v[198:201], v[98:113]
	v_mfma_f32_32x32x16_bf16 v[66:81], v[156:159], v[198:201], v[66:81]
	v_mfma_f32_32x32x16_bf16 v[98:113], v[142:145], v[228:231], v[98:113]
	v_mfma_f32_32x32x16_bf16 v[66:81], v[160:163], v[228:231], v[66:81]
	s_barrier
	s_add_u32 m0, s100, 0x0
	s_nop 0
	global_load_lds_dwordx4 v232, s[6:7]
	v_add_u32_e32 v232, 0x80, v232
	v_add3_u32 v246, v244, v240, 0
	v_add3_u32 v247, v244, v241, 0
	v_add3_u32 v248, v244, v242, 0
	v_add3_u32 v249, v244, v243, 0
	ds_read_b128 v[130:133], v246 offset:16384
	ds_read_b128 v[134:137], v247 offset:16384
	ds_read_b128 v[138:141], v248 offset:16384
	ds_read_b128 v[142:145], v249 offset:16384
	ds_read_b128 v[146:149], v246 offset:20480
	ds_read_b128 v[150:153], v247 offset:20480
	ds_read_b128 v[156:159], v248 offset:20480
	ds_read_b128 v[160:163], v249 offset:20480
	s_add_u32 m0, s100, 0x2000
	s_nop 0
	global_load_lds_dwordx4 v234, s[6:7]
	v_add_u32_e32 v234, 0x80, v234
	s_barrier
	s_waitcnt lgkmcnt(0)
	v_mfma_f32_32x32x16_bf16 v[50:65], v[130:133], v[170:173], v[50:65]
	v_mfma_f32_32x32x16_bf16 v[18:33], v[146:149], v[170:173], v[18:33]
	v_mfma_f32_32x32x16_bf16 v[50:65], v[134:137], v[174:177], v[50:65]
	v_mfma_f32_32x32x16_bf16 v[18:33], v[150:153], v[174:177], v[18:33]
	v_mfma_f32_32x32x16_bf16 v[50:65], v[138:141], v[178:181], v[50:65]
	v_mfma_f32_32x32x16_bf16 v[18:33], v[156:159], v[178:181], v[18:33]
	v_mfma_f32_32x32x16_bf16 v[50:65], v[142:145], v[186:189], v[50:65]
	v_mfma_f32_32x32x16_bf16 v[18:33], v[160:163], v[186:189], v[18:33]
	s_barrier
	s_add_u32 m0, s100, 0xc000
	s_nop 0
	global_load_lds_dwordx4 v237, s[8:9]
	v_add_u32_e32 v237, 0x80, v237
	s_add_u32 m0, s100, 0xe000
	s_nop 0
	global_load_lds_dwordx4 v239, s[8:9]
	v_add_u32_e32 v239, 0x80, v239
	s_waitcnt vmcnt(6)
	s_barrier
	v_mfma_f32_32x32x16_bf16 v[34:49], v[130:133], v[190:193], v[34:49]
	v_mfma_f32_32x32x16_bf16 v[2:17], v[146:149], v[190:193], v[2:17]
	v_mfma_f32_32x32x16_bf16 v[34:49], v[134:137], v[194:197], v[34:49]
	v_mfma_f32_32x32x16_bf16 v[2:17], v[150:153], v[194:197], v[2:17]
	v_mfma_f32_32x32x16_bf16 v[34:49], v[138:141], v[198:201], v[34:49]
	v_mfma_f32_32x32x16_bf16 v[2:17], v[156:159], v[198:201], v[2:17]
	v_mfma_f32_32x32x16_bf16 v[34:49], v[142:145], v[228:231], v[34:49]
	v_mfma_f32_32x32x16_bf16 v[2:17], v[160:163], v[228:231], v[2:17]
	s_barrier
	s_add_u32 m0, s100, 0x4000
	s_nop 0
	global_load_lds_dwordx4 v233, s[6:7]
	v_add_u32_e32 v233, 0x80, v233
	v_add3_u32 v246, v245, v240, s10
	v_add3_u32 v247, v245, v241, s10
	v_add3_u32 v248, v245, v242, s10
	v_add3_u32 v249, v245, v243, s10
	ds_read_b128 v[170:173], v246 offset:32768
	ds_read_b128 v[174:177], v247 offset:32768
	ds_read_b128 v[178:181], v248 offset:32768
	ds_read_b128 v[186:189], v249 offset:32768
	v_add3_u32 v246, v244, v240, s10
	v_add3_u32 v247, v244, v241, s10
	v_add3_u32 v248, v244, v242, s10
	v_add3_u32 v249, v244, v243, s10
	ds_read_b128 v[130:133], v246
	ds_read_b128 v[134:137], v247
	ds_read_b128 v[138:141], v248
	ds_read_b128 v[142:145], v249
	ds_read_b128 v[146:149], v246 offset:4096
	ds_read_b128 v[150:153], v247 offset:4096
	ds_read_b128 v[156:159], v248 offset:4096
	ds_read_b128 v[160:163], v249 offset:4096
	s_add_u32 m0, s100, 0x6000
	s_nop 0
	global_load_lds_dwordx4 v235, s[6:7]
	v_add_u32_e32 v235, 0x80, v235
	s_waitcnt lgkmcnt(8)
	s_barrier
; template <bool SWAP>
; DI void gemm_mainloop(f32x16 (&acc)[4][2], const u16* __restrict__ A, int lda, int rlo, int rhi,
;                       const u16* __restrict__ B, int ldb, int K, char* lds, const u16* zero_line) {
;     ...
; #pragma unroll 2
;   for (int kt = 0; kt < nk; ++kt) {
;     const char* st = lds + (kt & 1) * 65536;
;     ldfrag(st, 0, 0);
;     mma(1);
;     pat_rd();
;     if (kt + 1 < nk) glds(kt + 1, (kt + 1) & 1);
;     ldfrag(st, 1, 1);
;     mma(0);
;     pat_rd();
;     ldfrag(st, 2, 0);
;     mma(1);
;     pat_rd();
;     ldfrag(st, 3, 1);
;     mma(0);
;     pat_rd();
;     asm volatile("s_waitcnt vmcnt(0)" ::: "memory");
;     __syncthreads();
;   }
	s_waitcnt lgkmcnt(0)
	v_mfma_f32_32x32x16_bf16 v[114:129], v[130:133], v[170:173], v[114:129]
	v_mfma_f32_32x32x16_bf16 v[82:97], v[146:149], v[170:173], v[82:97]
	v_mfma_f32_32x32x16_bf16 v[114:129], v[134:137], v[174:177], v[114:129]
	v_mfma_f32_32x32x16_bf16 v[82:97], v[150:153], v[174:177], v[82:97]
	v_mfma_f32_32x32x16_bf16 v[114:129], v[138:141], v[178:181], v[114:129]
	v_mfma_f32_32x32x16_bf16 v[82:97], v[156:159], v[178:181], v[82:97]
	v_mfma_f32_32x32x16_bf16 v[114:129], v[142:145], v[186:189], v[114:129]
	v_mfma_f32_32x32x16_bf16 v[82:97], v[160:163], v[186:189], v[82:97]
	s_barrier
	s_add_u32 m0, s100, 0x18000
	s_nop 0
	global_load_lds_dwordx4 v236, s[8:9]
	v_add_u32_e32 v236, 0x80, v236
	v_add3_u32 v246, v245, v240, s10
	v_add3_u32 v247, v245, v241, s10
	v_add3_u32 v248, v245, v242, s10
	v_add3_u32 v249, v245, v243, s10
	ds_read_b128 v[190:193], v246 offset:49152
	ds_read_b128 v[194:197], v247 offset:49152
	ds_read_b128 v[198:201], v248 offset:49152
	ds_read_b128 v[228:231], v249 offset:49152
	s_add_u32 m0, s100, 0x1a000
	s_nop 0
	global_load_lds_dwordx4 v238, s[8:9]
	v_add_u32_e32 v238, 0x80, v238
	s_barrier
	s_waitcnt lgkmcnt(0)
	v_mfma_f32_32x32x16_bf16 v[98:113], v[130:133], v[190:193], v[98:113]
	v_mfma_f32_32x32x16_bf16 v[66:81], v[146:149], v[190:193], v[66:81]
	v_mfma_f32_32x32x16_bf16 v[98:113], v[134:137], v[194:197], v[98:113]
	v_mfma_f32_32x32x16_bf16 v[66:81], v[150:153], v[194:197], v[66:81]
	v_mfma_f32_32x32x16_bf16 v[98:113], v[138:141], v[198:201], v[98:113]
	v_mfma_f32_32x32x16_bf16 v[66:81], v[156:159], v[198:201], v[66:81]
	v_mfma_f32_32x32x16_bf16 v[98:113], v[142:145], v[228:231], v[98:113]
	v_mfma_f32_32x32x16_bf16 v[66:81], v[160:163], v[228:231], v[66:81]
	s_barrier
	s_add_u32 m0, s100, 0x10000
	s_nop 0
	global_load_lds_dwordx4 v232, s[6:7]
	v_add_u32_e32 v232, 0x80, v232
	v_add3_u32 v246, v244, v240, s10
	v_add3_u32 v247, v244, v241, s10
	v_add3_u32 v248, v244, v242, s10
	v_add3_u32 v249, v244, v243, s10
	ds_read_b128 v[130:133], v246 offset:16384
	ds_read_b128 v[134:137], v247 offset:16384
	ds_read_b128 v[138:141], v248 offset:16384
	ds_read_b128 v[142:145], v249 offset:16384
	ds_read_b128 v[146:149], v246 offset:20480
	ds_read_b128 v[150:153], v247 offset:20480
	ds_read_b128 v[156:159], v248 offset:20480
	ds_read_b128 v[160:163], v249 offset:20480
	s_add_u32 m0, s100, 0x12000
	s_nop 0
	global_load_lds_dwordx4 v234, s[6:7]
	v_add_u32_e32 v234, 0x80, v234
	s_barrier
	s_waitcnt lgkmcnt(0)
	v_mfma_f32_32x32x16_bf16 v[50:65], v[130:133], v[170:173], v[50:65]
	v_mfma_f32_32x32x16_bf16 v[18:33], v[146:149], v[170:173], v[18:33]
	v_mfma_f32_32x32x16_bf16 v[50:65], v[134:137], v[174:177], v[50:65]
	v_mfma_f32_32x32x16_bf16 v[18:33], v[150:153], v[174:177], v[18:33]
	v_mfma_f32_32x32x16_bf16 v[50:65], v[138:141], v[178:181], v[50:65]
	v_mfma_f32_32x32x16_bf16 v[18:33], v[156:159], v[178:181], v[18:33]
	v_mfma_f32_32x32x16_bf16 v[50:65], v[142:145], v[186:189], v[50:65]
	v_mfma_f32_32x32x16_bf16 v[18:33], v[160:163], v[186:189], v[18:33]
	s_barrier
	s_add_u32 m0, s100, 0x1c000
	s_nop 0
	global_load_lds_dwordx4 v237, s[8:9]
	v_add_u32_e32 v237, 0x80, v237
	s_add_u32 m0, s100, 0x1e000
	s_nop 0
	global_load_lds_dwordx4 v239, s[8:9]
	v_add_u32_e32 v239, 0x80, v239
	s_waitcnt vmcnt(6)
	s_barrier
	v_mfma_f32_32x32x16_bf16 v[34:49], v[130:133], v[190:193], v[34:49]
	v_mfma_f32_32x32x16_bf16 v[2:17], v[146:149], v[190:193], v[2:17]
	v_mfma_f32_32x32x16_bf16 v[34:49], v[134:137], v[194:197], v[34:49]
	v_mfma_f32_32x32x16_bf16 v[2:17], v[150:153], v[194:197], v[2:17]
	v_mfma_f32_32x32x16_bf16 v[34:49], v[138:141], v[198:201], v[34:49]
	v_mfma_f32_32x32x16_bf16 v[2:17], v[156:159], v[198:201], v[2:17]
	v_mfma_f32_32x32x16_bf16 v[34:49], v[142:145], v[228:231], v[34:49]
	v_mfma_f32_32x32x16_bf16 v[2:17], v[160:163], v[228:231], v[2:17]
	s_barrier
	s_add_i32 s11, s11, 2
	s_cmp_lt_u32 s11, 14
	s_cbranch_scc1 .Lg8_qa
	v_add3_u32 v246, v245, v240, 0
	v_add3_u32 v247, v245, v241, 0
	v_add3_u32 v248, v245, v242, 0
	v_add3_u32 v249, v245, v243, 0
	ds_read_b128 v[170:173], v246 offset:32768
	ds_read_b128 v[174:177], v247 offset:32768
	ds_read_b128 v[178:181], v248 offset:32768
	ds_read_b128 v[186:189], v249 offset:32768
	v_add3_u32 v246, v244, v240, 0
	v_add3_u32 v247, v244, v241, 0
	v_add3_u32 v248, v244, v242, 0
	v_add3_u32 v249, v244, v243, 0
	ds_read_b128 v[130:133], v246
	ds_read_b128 v[134:137], v247
	ds_read_b128 v[138:141], v248
	ds_read_b128 v[142:145], v249
	ds_read_b128 v[146:149], v246 offset:4096
	ds_read_b128 v[150:153], v247 offset:4096
	ds_read_b128 v[156:159], v248 offset:4096
	ds_read_b128 v[160:163], v249 offset:4096
	s_add_u32 m0, s100, 0x14000
	s_nop 0
	global_load_lds_dwordx4 v233, s[6:7]
	v_add_u32_e32 v233, 0x80, v233
	s_add_u32 m0, s100, 0x16000
	s_nop 0
	global_load_lds_dwordx4 v235, s[6:7]
	v_add_u32_e32 v235, 0x80, v235
	s_barrier
	s_waitcnt lgkmcnt(0)
	v_mfma_f32_32x32x16_bf16 v[114:129], v[130:133], v[170:173], v[114:129]
	v_mfma_f32_32x32x16_bf16 v[82:97], v[146:149], v[170:173], v[82:97]
	v_mfma_f32_32x32x16_bf16 v[114:129], v[134:137], v[174:177], v[114:129]
	v_mfma_f32_32x32x16_bf16 v[82:97], v[150:153], v[174:177], v[82:97]
	v_mfma_f32_32x32x16_bf16 v[114:129], v[138:141], v[178:181], v[114:129]
	v_mfma_f32_32x32x16_bf16 v[82:97], v[156:159], v[178:181], v[82:97]
	v_mfma_f32_32x32x16_bf16 v[114:129], v[142:145], v[186:189], v[114:129]
	v_mfma_f32_32x32x16_bf16 v[82:97], v[160:163], v[186:189], v[82:97]
	s_barrier
	v_add3_u32 v246, v245, v240, 0
	v_add3_u32 v247, v245, v241, 0
	v_add3_u32 v248, v245, v242, 0
	v_add3_u32 v249, v245, v243, 0
	ds_read_b128 v[190:193], v246 offset:49152
	ds_read_b128 v[194:197], v247 offset:49152
	ds_read_b128 v[198:201], v248 offset:49152
	ds_read_b128 v[228:231], v249 offset:49152
	s_barrier
; template <bool SWAP>
; DI void gemm_mainloop(f32x16 (&acc)[4][2], const u16* __restrict__ A, int lda, int rlo, int rhi,
;                       const u16* __restrict__ B, int ldb, int K, char* lds, const u16* zero_line) {
;     ...
; #pragma unroll 2
;   for (int kt = 0; kt < nk; ++kt) {
;     const char* st = lds + (kt & 1) * 65536;
;     ldfrag(st, 0, 0);
;     mma(1);
;     pat_rd();
;     if (kt + 1 < nk) glds(kt + 1, (kt + 1) & 1);
;     ldfrag(st, 1, 1);
;     mma(0);
;     pat_rd();
;     ldfrag(st, 2, 0);
;     mma(1);
;     pat_rd();
;     ldfrag(st, 3, 1);
;     mma(0);
;     pat_rd();
;     asm volatile("s_waitcnt vmcnt(0)" ::: "memory");
;     __syncthreads();
;   }
;   mma(1);
	s_waitcnt lgkmcnt(0)
	v_mfma_f32_32x32x16_bf16 v[98:113], v[130:133], v[190:193], v[98:113]
	v_mfma_f32_32x32x16_bf16 v[66:81], v[146:149], v[190:193], v[66:81]
	v_mfma_f32_32x32x16_bf16 v[98:113], v[134:137], v[194:197], v[98:113]
	v_mfma_f32_32x32x16_bf16 v[66:81], v[150:153], v[194:197], v[66:81]
	v_mfma_f32_32x32x16_bf16 v[98:113], v[138:141], v[198:201], v[98:113]
	v_mfma_f32_32x32x16_bf16 v[66:81], v[156:159], v[198:201], v[66:81]
	v_mfma_f32_32x32x16_bf16 v[98:113], v[142:145], v[228:231], v[98:113]
	v_mfma_f32_32x32x16_bf16 v[66:81], v[160:163], v[228:231], v[66:81]
	s_barrier
	v_add3_u32 v246, v244, v240, 0
	v_add3_u32 v247, v244, v241, 0
	v_add3_u32 v248, v244, v242, 0
	v_add3_u32 v249, v244, v243, 0
	ds_read_b128 v[130:133], v246 offset:16384
	ds_read_b128 v[134:137], v247 offset:16384
	ds_read_b128 v[138:141], v248 offset:16384
	ds_read_b128 v[142:145], v249 offset:16384
	ds_read_b128 v[146:149], v246 offset:20480
	ds_read_b128 v[150:153], v247 offset:20480
	ds_read_b128 v[156:159], v248 offset:20480
	ds_read_b128 v[160:163], v249 offset:20480
	s_waitcnt vmcnt(4)
	s_barrier
	s_waitcnt lgkmcnt(0)
	v_mfma_f32_32x32x16_bf16 v[50:65], v[130:133], v[170:173], v[50:65]
	v_mfma_f32_32x32x16_bf16 v[18:33], v[146:149], v[170:173], v[18:33]
	v_mfma_f32_32x32x16_bf16 v[50:65], v[134:137], v[174:177], v[50:65]
	v_mfma_f32_32x32x16_bf16 v[18:33], v[150:153], v[174:177], v[18:33]
	v_mfma_f32_32x32x16_bf16 v[50:65], v[138:141], v[178:181], v[50:65]
	v_mfma_f32_32x32x16_bf16 v[18:33], v[156:159], v[178:181], v[18:33]
	v_mfma_f32_32x32x16_bf16 v[50:65], v[142:145], v[186:189], v[50:65]
	v_mfma_f32_32x32x16_bf16 v[18:33], v[160:163], v[186:189], v[18:33]
	v_mfma_f32_32x32x16_bf16 v[34:49], v[130:133], v[190:193], v[34:49]
	v_mfma_f32_32x32x16_bf16 v[2:17], v[146:149], v[190:193], v[2:17]
	v_mfma_f32_32x32x16_bf16 v[34:49], v[134:137], v[194:197], v[34:49]
	v_mfma_f32_32x32x16_bf16 v[2:17], v[150:153], v[194:197], v[2:17]
	v_mfma_f32_32x32x16_bf16 v[34:49], v[138:141], v[198:201], v[34:49]
	v_mfma_f32_32x32x16_bf16 v[2:17], v[156:159], v[198:201], v[2:17]
	v_mfma_f32_32x32x16_bf16 v[34:49], v[142:145], v[228:231], v[34:49]
	v_mfma_f32_32x32x16_bf16 v[2:17], v[160:163], v[228:231], v[2:17]
	s_barrier
	v_add3_u32 v246, v245, v240, s10
	v_add3_u32 v247, v245, v241, s10
	v_add3_u32 v248, v245, v242, s10
	v_add3_u32 v249, v245, v243, s10
	ds_read_b128 v[170:173], v246 offset:32768
	ds_read_b128 v[174:177], v247 offset:32768
	ds_read_b128 v[178:181], v248 offset:32768
	ds_read_b128 v[186:189], v249 offset:32768
	v_add3_u32 v246, v244, v240, s10
	v_add3_u32 v247, v244, v241, s10
	v_add3_u32 v248, v244, v242, s10
	v_add3_u32 v249, v244, v243, s10
	ds_read_b128 v[130:133], v246
	ds_read_b128 v[134:137], v247
	ds_read_b128 v[138:141], v248
	ds_read_b128 v[142:145], v249
	ds_read_b128 v[146:149], v246 offset:4096
	ds_read_b128 v[150:153], v247 offset:4096
	ds_read_b128 v[156:159], v248 offset:4096
	ds_read_b128 v[160:163], v249 offset:4096
	s_waitcnt vmcnt(2)
	s_barrier
	s_waitcnt lgkmcnt(0)
	v_mfma_f32_32x32x16_bf16 v[114:129], v[130:133], v[170:173], v[114:129]
	v_mfma_f32_32x32x16_bf16 v[82:97], v[146:149], v[170:173], v[82:97]
	v_mfma_f32_32x32x16_bf16 v[114:129], v[134:137], v[174:177], v[114:129]
	v_mfma_f32_32x32x16_bf16 v[82:97], v[150:153], v[174:177], v[82:97]
	v_mfma_f32_32x32x16_bf16 v[114:129], v[138:141], v[178:181], v[114:129]
	v_mfma_f32_32x32x16_bf16 v[82:97], v[156:159], v[178:181], v[82:97]
	v_mfma_f32_32x32x16_bf16 v[114:129], v[142:145], v[186:189], v[114:129]
	v_mfma_f32_32x32x16_bf16 v[82:97], v[160:163], v[186:189], v[82:97]
	s_barrier
	v_add3_u32 v246, v245, v240, s10
	v_add3_u32 v247, v245, v241, s10
	v_add3_u32 v248, v245, v242, s10
	v_add3_u32 v249, v245, v243, s10
	ds_read_b128 v[190:193], v246 offset:49152
	ds_read_b128 v[194:197], v247 offset:49152
	ds_read_b128 v[198:201], v248 offset:49152
	ds_read_b128 v[228:231], v249 offset:49152
	s_waitcnt vmcnt(0)
	s_barrier
	s_waitcnt lgkmcnt(0)
	v_mfma_f32_32x32x16_bf16 v[98:113], v[130:133], v[190:193], v[98:113]
	v_mfma_f32_32x32x16_bf16 v[66:81], v[146:149], v[190:193], v[66:81]
	v_mfma_f32_32x32x16_bf16 v[98:113], v[134:137], v[194:197], v[98:113]
	v_mfma_f32_32x32x16_bf16 v[66:81], v[150:153], v[194:197], v[66:81]
	v_mfma_f32_32x32x16_bf16 v[98:113], v[138:141], v[198:201], v[98:113]
	v_mfma_f32_32x32x16_bf16 v[66:81], v[156:159], v[198:201], v[66:81]
	v_mfma_f32_32x32x16_bf16 v[98:113], v[142:145], v[228:231], v[98:113]
	v_mfma_f32_32x32x16_bf16 v[66:81], v[160:163], v[228:231], v[66:81]
	s_barrier
	v_add3_u32 v246, v244, v240, s10
	v_add3_u32 v247, v244, v241, s10
	v_add3_u32 v248, v244, v242, s10
	v_add3_u32 v249, v244, v243, s10
	ds_read_b128 v[130:133], v246 offset:16384
	ds_read_b128 v[134:137], v247 offset:16384
	ds_read_b128 v[138:141], v248 offset:16384
	ds_read_b128 v[142:145], v249 offset:16384
	ds_read_b128 v[146:149], v246 offset:20480
	ds_read_b128 v[150:153], v247 offset:20480
	ds_read_b128 v[156:159], v248 offset:20480
	ds_read_b128 v[160:163], v249 offset:20480
	s_barrier
	s_waitcnt lgkmcnt(0)
	v_mfma_f32_32x32x16_bf16 v[50:65], v[130:133], v[170:173], v[50:65]
	v_mfma_f32_32x32x16_bf16 v[18:33], v[146:149], v[170:173], v[18:33]
	v_mfma_f32_32x32x16_bf16 v[50:65], v[134:137], v[174:177], v[50:65]
	v_mfma_f32_32x32x16_bf16 v[18:33], v[150:153], v[174:177], v[18:33]
	v_mfma_f32_32x32x16_bf16 v[50:65], v[138:141], v[178:181], v[50:65]
	v_mfma_f32_32x32x16_bf16 v[18:33], v[156:159], v[178:181], v[18:33]
	v_mfma_f32_32x32x16_bf16 v[50:65], v[142:145], v[186:189], v[50:65]
	v_mfma_f32_32x32x16_bf16 v[18:33], v[160:163], v[186:189], v[18:33]
	v_mfma_f32_32x32x16_bf16 v[34:49], v[130:133], v[190:193], v[34:49]
	v_mfma_f32_32x32x16_bf16 v[2:17], v[146:149], v[190:193], v[2:17]
	v_mfma_f32_32x32x16_bf16 v[34:49], v[134:137], v[194:197], v[34:49]
	v_mfma_f32_32x32x16_bf16 v[2:17], v[150:153], v[194:197], v[2:17]
	v_mfma_f32_32x32x16_bf16 v[34:49], v[138:141], v[198:201], v[34:49]
	v_mfma_f32_32x32x16_bf16 v[2:17], v[156:159], v[198:201], v[2:17]
	v_mfma_f32_32x32x16_bf16 v[34:49], v[142:145], v[228:231], v[34:49]
	v_mfma_f32_32x32x16_bf16 v[2:17], v[160:163], v[228:231], v[2:17]
	s_barrier
	s_cmp_eq_u32 s101, 0
	s_cbranch_scc0 .Lg8_qa_p1
	s_barrier

; template <bool SWAP>
; DI void gemm_mainloop(f32x16 (&acc)[4][2], const u16* __restrict__ A, int lda, int rlo, int rhi,
;                       const u16* __restrict__ B, int ldb, int K, char* lds, const u16* zero_line) {
;     ...
;   auto glds = [&](int kt, int st) {
;     char* as_ = lds + st * 65536 + tid * 16;
; #pragma unroll
;     for (int i = 0; i < 4; ++i) {
;       const int rr = lr + 64 * i;
;       const u16* srca = (rr >= rlo && rr < rhi) ? (ap + (ptrdiff_t)(64 * i) * lda + kt * 64) : (zero_line + lc * 8);
;       __builtin_amdgcn_global_load_lds((const unsigned*)srca, (lds_u32*)(as_ + i * 8192), 16, 0, 0);
;       __builtin_amdgcn_global_load_lds((const unsigned*)(bp + (ptrdiff_t)(64 * i) * ldb + kt * 64), (lds_u32*)(as_ + 32768 + i * 8192), 16, 0, 0);
;     }
;   };
;     ...
; #pragma unroll 2
;   for (int kt = 0; kt < nk; ++kt) {
;     const char* st = lds + (kt & 1) * 65536;
;     ldfrag(st, 0, 0);
;     mma(1);
;     pat_rd();
;     if (kt + 1 < nk) glds(kt + 1, (kt + 1) & 1);
;     ldfrag(st, 1, 1);
;     mma(0);
;     pat_rd();
;     ldfrag(st, 2, 0);
;     mma(1);
;     pat_rd();
;     ldfrag(st, 3, 1);
;     mma(0);
;     pat_rd();
;     asm volatile("s_waitcnt vmcnt(0)" ::: "memory");
;     __syncthreads();
.Lg8_qb:
	s_add_u32 m0, s100, 0x14000
	s_nop 0
	global_load_lds_dwordx4 v233, s[6:7]
	v_add_u32_e32 v233, 0x80, v233
	v_add3_u32 v246, v245, v240, 0
	v_add3_u32 v247, v245, v241, 0
	v_add3_u32 v248, v245, v242, 0
	v_add3_u32 v249, v245, v243, 0
	ds_read_b128 v[170:173], v246 offset:32768
	ds_read_b128 v[174:177], v247 offset:32768
	ds_read_b128 v[178:181], v248 offset:32768
	ds_read_b128 v[186:189], v249 offset:32768
	v_add3_u32 v246, v244, v240, 0
	v_add3_u32 v247, v244, v241, 0
	v_add3_u32 v248, v244, v242, 0
	v_add3_u32 v249, v244, v243, 0
	ds_read_b128 v[130:133], v246
	ds_read_b128 v[134:137], v247
	ds_read_b128 v[138:141], v248
	ds_read_b128 v[142:145], v249
	ds_read_b128 v[146:149], v246 offset:4096
	ds_read_b128 v[150:153], v247 offset:4096
	ds_read_b128 v[156:159], v248 offset:4096
	ds_read_b128 v[160:163], v249 offset:4096
	s_add_u32 m0, s100, 0x16000
	s_nop 0
	global_load_lds_dwordx4 v235, s[6:7]
	v_add_u32_e32 v235, 0x80, v235
	s_waitcnt lgkmcnt(8)
	s_barrier
	s_waitcnt lgkmcnt(0)
	v_mfma_f32_32x32x16_bf16 v[114:129], v[170:173], v[130:133], v[114:129]
	v_mfma_f32_32x32x16_bf16 v[82:97], v[170:173], v[146:149], v[82:97]
	v_mfma_f32_32x32x16_bf16 v[114:129], v[174:177], v[134:137], v[114:129]
	v_mfma_f32_32x32x16_bf16 v[82:97], v[174:177], v[150:153], v[82:97]
	v_mfma_f32_32x32x16_bf16 v[114:129], v[178:181], v[138:141], v[114:129]
	v_mfma_f32_32x32x16_bf16 v[82:97], v[178:181], v[156:159], v[82:97]
	v_mfma_f32_32x32x16_bf16 v[114:129], v[186:189], v[142:145], v[114:129]
	v_mfma_f32_32x32x16_bf16 v[82:97], v[186:189], v[160:163], v[82:97]
	s_barrier
	s_add_u32 m0, s100, 0x8000
	s_nop 0
	global_load_lds_dwordx4 v236, s[8:9]
	v_add_u32_e32 v236, 0x80, v236
	v_add3_u32 v246, v245, v240, 0
	v_add3_u32 v247, v245, v241, 0
	v_add3_u32 v248, v245, v242, 0
	v_add3_u32 v249, v245, v243, 0
	ds_read_b128 v[190:193], v246 offset:49152
	ds_read_b128 v[194:197], v247 offset:49152
	ds_read_b128 v[198:201], v248 offset:49152
	ds_read_b128 v[228:231], v249 offset:49152
	s_add_u32 m0, s100, 0xa000
	s_nop 0
	global_load_lds_dwordx4 v238, s[8:9]
	v_add_u32_e32 v238, 0x80, v238
	s_barrier
	s_waitcnt lgkmcnt(0)
	v_mfma_f32_32x32x16_bf16 v[98:113], v[190:193], v[130:133], v[98:113]
	v_mfma_f32_32x32x16_bf16 v[66:81], v[190:193], v[146:149], v[66:81]
	v_mfma_f32_32x32x16_bf16 v[98:113], v[194:197], v[134:137], v[98:113]
	v_mfma_f32_32x32x16_bf16 v[66:81], v[194:197], v[150:153], v[66:81]
	v_mfma_f32_32x32x16_bf16 v[98:113], v[198:201], v[138:141], v[98:113]
	v_mfma_f32_32x32x16_bf16 v[66:81], v[198:201], v[156:159], v[66:81]
	v_mfma_f32_32x32x16_bf16 v[98:113], v[228:231], v[142:145], v[98:113]
	v_mfma_f32_32x32x16_bf16 v[66:81], v[228:231], v[160:163], v[66:81]
	s_barrier
	s_add_u32 m0, s100, 0x0
	s_nop 0
	global_load_lds_dwordx4 v232, s[6:7]
	v_add_u32_e32 v232, 0x80, v232
	v_add3_u32 v246, v244, v240, 0
	v_add3_u32 v247, v244, v241, 0
	v_add3_u32 v248, v244, v242, 0
	v_add3_u32 v249, v244, v243, 0
	ds_read_b128 v[130:133], v246 offset:16384
	ds_read_b128 v[134:137], v247 offset:16384
	ds_read_b128 v[138:141], v248 offset:16384
	ds_read_b128 v[142:145], v249 offset:16384
	ds_read_b128 v[146:149], v246 offset:20480
	ds_read_b128 v[150:153], v247 offset:20480
	ds_read_b128 v[156:159], v248 offset:20480
	ds_read_b128 v[160:163], v249 offset:20480
	s_add_u32 m0, s100, 0x2000
	s_nop 0
	global_load_lds_dwordx4 v234, s[6:7]
	v_add_u32_e32 v234, 0x80, v234
	s_barrier
	s_waitcnt lgkmcnt(0)
	v_mfma_f32_32x32x16_bf16 v[50:65], v[170:173], v[130:133], v[50:65]
	v_mfma_f32_32x32x16_bf16 v[18:33], v[170:173], v[146:149], v[18:33]
	v_mfma_f32_32x32x16_bf16 v[50:65], v[174:177], v[134:137], v[50:65]
	v_mfma_f32_32x32x16_bf16 v[18:33], v[174:177], v[150:153], v[18:33]
	v_mfma_f32_32x32x16_bf16 v[50:65], v[178:181], v[138:141], v[50:65]
	v_mfma_f32_32x32x16_bf16 v[18:33], v[178:181], v[156:159], v[18:33]
	v_mfma_f32_32x32x16_bf16 v[50:65], v[186:189], v[142:145], v[50:65]
	v_mfma_f32_32x32x16_bf16 v[18:33], v[186:189], v[160:163], v[18:33]
	s_barrier
	s_add_u32 m0, s100, 0xc000
	s_nop 0
	global_load_lds_dwordx4 v237, s[8:9]
	v_add_u32_e32 v237, 0x80, v237
	s_add_u32 m0, s100, 0xe000
	s_nop 0
	global_load_lds_dwordx4 v239, s[8:9]
	v_add_u32_e32 v239, 0x80, v239
	s_waitcnt vmcnt(6)
	s_barrier
	v_mfma_f32_32x32x16_bf16 v[34:49], v[190:193], v[130:133], v[34:49]
	v_mfma_f32_32x32x16_bf16 v[2:17], v[190:193], v[146:149], v[2:17]
	v_mfma_f32_32x32x16_bf16 v[34:49], v[194:197], v[134:137], v[34:49]
	v_mfma_f32_32x32x16_bf16 v[2:17], v[194:197], v[150:153], v[2:17]
	v_mfma_f32_32x32x16_bf16 v[34:49], v[198:201], v[138:141], v[34:49]
	v_mfma_f32_32x32x16_bf16 v[2:17], v[198:201], v[156:159], v[2:17]
	v_mfma_f32_32x32x16_bf16 v[34:49], v[228:231], v[142:145], v[34:49]
	v_mfma_f32_32x32x16_bf16 v[2:17], v[228:231], v[160:163], v[2:17]
	s_barrier
	s_add_u32 m0, s100, 0x4000
	s_nop 0
	global_load_lds_dwordx4 v233, s[6:7]
	v_add_u32_e32 v233, 0x80, v233
	v_add3_u32 v246, v245, v240, s10
	v_add3_u32 v247, v245, v241, s10
	v_add3_u32 v248, v245, v242, s10
	v_add3_u32 v249, v245, v243, s10
	ds_read_b128 v[170:173], v246 offset:32768
	ds_read_b128 v[174:177], v247 offset:32768
	ds_read_b128 v[178:181], v248 offset:32768
	ds_read_b128 v[186:189], v249 offset:32768
	v_add3_u32 v246, v244, v240, s10
	v_add3_u32 v247, v244, v241, s10
	v_add3_u32 v248, v244, v242, s10
	v_add3_u32 v249, v244, v243, s10
	ds_read_b128 v[130:133], v246
	ds_read_b128 v[134:137], v247
	ds_read_b128 v[138:141], v248
	ds_read_b128 v[142:145], v249
	ds_read_b128 v[146:149], v246 offset:4096
	ds_read_b128 v[150:153], v247 offset:4096
	ds_read_b128 v[156:159], v248 offset:4096
	ds_read_b128 v[160:163], v249 offset:4096
	s_add_u32 m0, s100, 0x6000
	s_nop 0
	global_load_lds_dwordx4 v235, s[6:7]
	v_add_u32_e32 v235, 0x80, v235
	s_waitcnt lgkmcnt(8)
	s_barrier
; template <bool SWAP>
; DI void gemm_mainloop(f32x16 (&acc)[4][2], const u16* __restrict__ A, int lda, int rlo, int rhi,
;                       const u16* __restrict__ B, int ldb, int K, char* lds, const u16* zero_line) {
;     ...
; #pragma unroll 2
;   for (int kt = 0; kt < nk; ++kt) {
;     const char* st = lds + (kt & 1) * 65536;
;     ldfrag(st, 0, 0);
;     mma(1);
;     pat_rd();
;     if (kt + 1 < nk) glds(kt + 1, (kt + 1) & 1);
;     ldfrag(st, 1, 1);
;     mma(0);
;     pat_rd();
;     ldfrag(st, 2, 0);
;     mma(1);
;     pat_rd();
;     ldfrag(st, 3, 1);
;     mma(0);
;     pat_rd();
;     asm volatile("s_waitcnt vmcnt(0)" ::: "memory");
;     __syncthreads();
;   }
	s_waitcnt lgkmcnt(0)
	v_mfma_f32_32x32x16_bf16 v[114:129], v[170:173], v[130:133], v[114:129]
	v_mfma_f32_32x32x16_bf16 v[82:97], v[170:173], v[146:149], v[82:97]
	v_mfma_f32_32x32x16_bf16 v[114:129], v[174:177], v[134:137], v[114:129]
	v_mfma_f32_32x32x16_bf16 v[82:97], v[174:177], v[150:153], v[82:97]
	v_mfma_f32_32x32x16_bf16 v[114:129], v[178:181], v[138:141], v[114:129]
	v_mfma_f32_32x32x16_bf16 v[82:97], v[178:181], v[156:159], v[82:97]
	v_mfma_f32_32x32x16_bf16 v[114:129], v[186:189], v[142:145], v[114:129]
	v_mfma_f32_32x32x16_bf16 v[82:97], v[186:189], v[160:163], v[82:97]
	s_barrier
	s_add_u32 m0, s100, 0x18000
	s_nop 0
	global_load_lds_dwordx4 v236, s[8:9]
	v_add_u32_e32 v236, 0x80, v236
	v_add3_u32 v246, v245, v240, s10
	v_add3_u32 v247, v245, v241, s10
	v_add3_u32 v248, v245, v242, s10
	v_add3_u32 v249, v245, v243, s10
	ds_read_b128 v[190:193], v246 offset:49152
	ds_read_b128 v[194:197], v247 offset:49152
	ds_read_b128 v[198:201], v248 offset:49152
	ds_read_b128 v[228:231], v249 offset:49152
	s_add_u32 m0, s100, 0x1a000
	s_nop 0
	global_load_lds_dwordx4 v238, s[8:9]
	v_add_u32_e32 v238, 0x80, v238
	s_barrier
	s_waitcnt lgkmcnt(0)
	v_mfma_f32_32x32x16_bf16 v[98:113], v[190:193], v[130:133], v[98:113]
	v_mfma_f32_32x32x16_bf16 v[66:81], v[190:193], v[146:149], v[66:81]
	v_mfma_f32_32x32x16_bf16 v[98:113], v[194:197], v[134:137], v[98:113]
	v_mfma_f32_32x32x16_bf16 v[66:81], v[194:197], v[150:153], v[66:81]
	v_mfma_f32_32x32x16_bf16 v[98:113], v[198:201], v[138:141], v[98:113]
	v_mfma_f32_32x32x16_bf16 v[66:81], v[198:201], v[156:159], v[66:81]
	v_mfma_f32_32x32x16_bf16 v[98:113], v[228:231], v[142:145], v[98:113]
	v_mfma_f32_32x32x16_bf16 v[66:81], v[228:231], v[160:163], v[66:81]
	s_barrier
	s_add_u32 m0, s100, 0x10000
	s_nop 0
	global_load_lds_dwordx4 v232, s[6:7]
	v_add_u32_e32 v232, 0x80, v232
	v_add3_u32 v246, v244, v240, s10
	v_add3_u32 v247, v244, v241, s10
	v_add3_u32 v248, v244, v242, s10
	v_add3_u32 v249, v244, v243, s10
	ds_read_b128 v[130:133], v246 offset:16384
	ds_read_b128 v[134:137], v247 offset:16384
	ds_read_b128 v[138:141], v248 offset:16384
	ds_read_b128 v[142:145], v249 offset:16384
	ds_read_b128 v[146:149], v246 offset:20480
	ds_read_b128 v[150:153], v247 offset:20480
	ds_read_b128 v[156:159], v248 offset:20480
	ds_read_b128 v[160:163], v249 offset:20480
	s_add_u32 m0, s100, 0x12000
	s_nop 0
	global_load_lds_dwordx4 v234, s[6:7]
	v_add_u32_e32 v234, 0x80, v234
	s_barrier
	s_waitcnt lgkmcnt(0)
	v_mfma_f32_32x32x16_bf16 v[50:65], v[170:173], v[130:133], v[50:65]
	v_mfma_f32_32x32x16_bf16 v[18:33], v[170:173], v[146:149], v[18:33]
	v_mfma_f32_32x32x16_bf16 v[50:65], v[174:177], v[134:137], v[50:65]
	v_mfma_f32_32x32x16_bf16 v[18:33], v[174:177], v[150:153], v[18:33]
	v_mfma_f32_32x32x16_bf16 v[50:65], v[178:181], v[138:141], v[50:65]
	v_mfma_f32_32x32x16_bf16 v[18:33], v[178:181], v[156:159], v[18:33]
	v_mfma_f32_32x32x16_bf16 v[50:65], v[186:189], v[142:145], v[50:65]
	v_mfma_f32_32x32x16_bf16 v[18:33], v[186:189], v[160:163], v[18:33]
	s_barrier
	s_add_u32 m0, s100, 0x1c000
	s_nop 0
	global_load_lds_dwordx4 v237, s[8:9]
	v_add_u32_e32 v237, 0x80, v237
	s_add_u32 m0, s100, 0x1e000
	s_nop 0
	global_load_lds_dwordx4 v239, s[8:9]
	v_add_u32_e32 v239, 0x80, v239
	s_waitcnt vmcnt(6)
	s_barrier
	v_mfma_f32_32x32x16_bf16 v[34:49], v[190:193], v[130:133], v[34:49]
	v_mfma_f32_32x32x16_bf16 v[2:17], v[190:193], v[146:149], v[2:17]
	v_mfma_f32_32x32x16_bf16 v[34:49], v[194:197], v[134:137], v[34:49]
	v_mfma_f32_32x32x16_bf16 v[2:17], v[194:197], v[150:153], v[2:17]
	v_mfma_f32_32x32x16_bf16 v[34:49], v[198:201], v[138:141], v[34:49]
	v_mfma_f32_32x32x16_bf16 v[2:17], v[198:201], v[156:159], v[2:17]
	v_mfma_f32_32x32x16_bf16 v[34:49], v[228:231], v[142:145], v[34:49]
	v_mfma_f32_32x32x16_bf16 v[2:17], v[228:231], v[160:163], v[2:17]
	s_barrier
	s_add_i32 s11, s11, 2
	s_cmp_lt_u32 s11, 14
	s_cbranch_scc1 .Lg8_qb
	v_add3_u32 v246, v245, v240, 0
	v_add3_u32 v247, v245, v241, 0
	v_add3_u32 v248, v245, v242, 0
	v_add3_u32 v249, v245, v243, 0
	ds_read_b128 v[170:173], v246 offset:32768
	ds_read_b128 v[174:177], v247 offset:32768
	ds_read_b128 v[178:181], v248 offset:32768
	ds_read_b128 v[186:189], v249 offset:32768
	v_add3_u32 v246, v244, v240, 0
	v_add3_u32 v247, v244, v241, 0
	v_add3_u32 v248, v244, v242, 0
	v_add3_u32 v249, v244, v243, 0
	ds_read_b128 v[130:133], v246
	ds_read_b128 v[134:137], v247
	ds_read_b128 v[138:141], v248
	ds_read_b128 v[142:145], v249
	ds_read_b128 v[146:149], v246 offset:4096
	ds_read_b128 v[150:153], v247 offset:4096
	ds_read_b128 v[156:159], v248 offset:4096
	ds_read_b128 v[160:163], v249 offset:4096
	s_add_u32 m0, s100, 0x14000
	s_nop 0
	global_load_lds_dwordx4 v233, s[6:7]
	v_add_u32_e32 v233, 0x80, v233
	s_add_u32 m0, s100, 0x16000
	s_nop 0
	global_load_lds_dwordx4 v235, s[6:7]
	v_add_u32_e32 v235, 0x80, v235
	s_barrier
	s_waitcnt lgkmcnt(0)
	v_mfma_f32_32x32x16_bf16 v[114:129], v[170:173], v[130:133], v[114:129]
	v_mfma_f32_32x32x16_bf16 v[82:97], v[170:173], v[146:149], v[82:97]
	v_mfma_f32_32x32x16_bf16 v[114:129], v[174:177], v[134:137], v[114:129]
	v_mfma_f32_32x32x16_bf16 v[82:97], v[174:177], v[150:153], v[82:97]
	v_mfma_f32_32x32x16_bf16 v[114:129], v[178:181], v[138:141], v[114:129]
	v_mfma_f32_32x32x16_bf16 v[82:97], v[178:181], v[156:159], v[82:97]
	v_mfma_f32_32x32x16_bf16 v[114:129], v[186:189], v[142:145], v[114:129]
	v_mfma_f32_32x32x16_bf16 v[82:97], v[186:189], v[160:163], v[82:97]
	s_barrier
	v_add3_u32 v246, v245, v240, 0
	v_add3_u32 v247, v245, v241, 0
	v_add3_u32 v248, v245, v242, 0
	v_add3_u32 v249, v245, v243, 0
	ds_read_b128 v[190:193], v246 offset:49152
	ds_read_b128 v[194:197], v247 offset:49152
	ds_read_b128 v[198:201], v248 offset:49152
	ds_read_b128 v[228:231], v249 offset:49152
	s_barrier
; template <bool SWAP>
; DI void gemm_mainloop(f32x16 (&acc)[4][2], const u16* __restrict__ A, int lda, int rlo, int rhi,
;                       const u16* __restrict__ B, int ldb, int K, char* lds, const u16* zero_line) {
;     ...
; #pragma unroll 2
;   for (int kt = 0; kt < nk; ++kt) {
;     const char* st = lds + (kt & 1) * 65536;
;     ldfrag(st, 0, 0);
;     mma(1);
;     pat_rd();
;     if (kt + 1 < nk) glds(kt + 1, (kt + 1) & 1);
;     ldfrag(st, 1, 1);
;     mma(0);
;     pat_rd();
;     ldfrag(st, 2, 0);
;     mma(1);
;     pat_rd();
;     ldfrag(st, 3, 1);
;     mma(0);
;     pat_rd();
;     asm volatile("s_waitcnt vmcnt(0)" ::: "memory");
;     __syncthreads();
;   }
;   mma(1);
	s_waitcnt lgkmcnt(0)
	v_mfma_f32_32x32x16_bf16 v[98:113], v[190:193], v[130:133], v[98:113]
	v_mfma_f32_32x32x16_bf16 v[66:81], v[190:193], v[146:149], v[66:81]
	v_mfma_f32_32x32x16_bf16 v[98:113], v[194:197], v[134:137], v[98:113]
	v_mfma_f32_32x32x16_bf16 v[66:81], v[194:197], v[150:153], v[66:81]
	v_mfma_f32_32x32x16_bf16 v[98:113], v[198:201], v[138:141], v[98:113]
	v_mfma_f32_32x32x16_bf16 v[66:81], v[198:201], v[156:159], v[66:81]
	v_mfma_f32_32x32x16_bf16 v[98:113], v[228:231], v[142:145], v[98:113]
	v_mfma_f32_32x32x16_bf16 v[66:81], v[228:231], v[160:163], v[66:81]
	s_barrier
	v_add3_u32 v246, v244, v240, 0
	v_add3_u32 v247, v244, v241, 0
	v_add3_u32 v248, v244, v242, 0
	v_add3_u32 v249, v244, v243, 0
	ds_read_b128 v[130:133], v246 offset:16384
	ds_read_b128 v[134:137], v247 offset:16384
	ds_read_b128 v[138:141], v248 offset:16384
	ds_read_b128 v[142:145], v249 offset:16384
	ds_read_b128 v[146:149], v246 offset:20480
	ds_read_b128 v[150:153], v247 offset:20480
	ds_read_b128 v[156:159], v248 offset:20480
	ds_read_b128 v[160:163], v249 offset:20480
	s_waitcnt vmcnt(4)
	s_barrier
	s_waitcnt lgkmcnt(0)
	v_mfma_f32_32x32x16_bf16 v[50:65], v[170:173], v[130:133], v[50:65]
	v_mfma_f32_32x32x16_bf16 v[18:33], v[170:173], v[146:149], v[18:33]
	v_mfma_f32_32x32x16_bf16 v[50:65], v[174:177], v[134:137], v[50:65]
	v_mfma_f32_32x32x16_bf16 v[18:33], v[174:177], v[150:153], v[18:33]
	v_mfma_f32_32x32x16_bf16 v[50:65], v[178:181], v[138:141], v[50:65]
	v_mfma_f32_32x32x16_bf16 v[18:33], v[178:181], v[156:159], v[18:33]
	v_mfma_f32_32x32x16_bf16 v[50:65], v[186:189], v[142:145], v[50:65]
	v_mfma_f32_32x32x16_bf16 v[18:33], v[186:189], v[160:163], v[18:33]
	v_mfma_f32_32x32x16_bf16 v[34:49], v[190:193], v[130:133], v[34:49]
	v_mfma_f32_32x32x16_bf16 v[2:17], v[190:193], v[146:149], v[2:17]
	v_mfma_f32_32x32x16_bf16 v[34:49], v[194:197], v[134:137], v[34:49]
	v_mfma_f32_32x32x16_bf16 v[2:17], v[194:197], v[150:153], v[2:17]
	v_mfma_f32_32x32x16_bf16 v[34:49], v[198:201], v[138:141], v[34:49]
	v_mfma_f32_32x32x16_bf16 v[2:17], v[198:201], v[156:159], v[2:17]
	v_mfma_f32_32x32x16_bf16 v[34:49], v[228:231], v[142:145], v[34:49]
	v_mfma_f32_32x32x16_bf16 v[2:17], v[228:231], v[160:163], v[2:17]
	s_barrier
	v_add3_u32 v246, v245, v240, s10
	v_add3_u32 v247, v245, v241, s10
	v_add3_u32 v248, v245, v242, s10
	v_add3_u32 v249, v245, v243, s10
	ds_read_b128 v[170:173], v246 offset:32768
	ds_read_b128 v[174:177], v247 offset:32768
	ds_read_b128 v[178:181], v248 offset:32768
	ds_read_b128 v[186:189], v249 offset:32768
	v_add3_u32 v246, v244, v240, s10
	v_add3_u32 v247, v244, v241, s10
	v_add3_u32 v248, v244, v242, s10
	v_add3_u32 v249, v244, v243, s10
	ds_read_b128 v[130:133], v246
	ds_read_b128 v[134:137], v247
	ds_read_b128 v[138:141], v248
	ds_read_b128 v[142:145], v249
	ds_read_b128 v[146:149], v246 offset:4096
	ds_read_b128 v[150:153], v247 offset:4096
	ds_read_b128 v[156:159], v248 offset:4096
	ds_read_b128 v[160:163], v249 offset:4096
	s_waitcnt vmcnt(2)
	s_barrier
	s_waitcnt lgkmcnt(0)
	v_mfma_f32_32x32x16_bf16 v[114:129], v[170:173], v[130:133], v[114:129]
	v_mfma_f32_32x32x16_bf16 v[82:97], v[170:173], v[146:149], v[82:97]
	v_mfma_f32_32x32x16_bf16 v[114:129], v[174:177], v[134:137], v[114:129]
	v_mfma_f32_32x32x16_bf16 v[82:97], v[174:177], v[150:153], v[82:97]
	v_mfma_f32_32x32x16_bf16 v[114:129], v[178:181], v[138:141], v[114:129]
	v_mfma_f32_32x32x16_bf16 v[82:97], v[178:181], v[156:159], v[82:97]
	v_mfma_f32_32x32x16_bf16 v[114:129], v[186:189], v[142:145], v[114:129]
	v_mfma_f32_32x32x16_bf16 v[82:97], v[186:189], v[160:163], v[82:97]
	s_barrier
	v_add3_u32 v246, v245, v240, s10
	v_add3_u32 v247, v245, v241, s10
	v_add3_u32 v248, v245, v242, s10
	v_add3_u32 v249, v245, v243, s10
	ds_read_b128 v[190:193], v246 offset:49152
	ds_read_b128 v[194:197], v247 offset:49152
	ds_read_b128 v[198:201], v248 offset:49152
	ds_read_b128 v[228:231], v249 offset:49152
	s_waitcnt vmcnt(0)
	s_barrier
	s_waitcnt lgkmcnt(0)
	v_mfma_f32_32x32x16_bf16 v[98:113], v[190:193], v[130:133], v[98:113]
	v_mfma_f32_32x32x16_bf16 v[66:81], v[190:193], v[146:149], v[66:81]
	v_mfma_f32_32x32x16_bf16 v[98:113], v[194:197], v[134:137], v[98:113]
	v_mfma_f32_32x32x16_bf16 v[66:81], v[194:197], v[150:153], v[66:81]
	v_mfma_f32_32x32x16_bf16 v[98:113], v[198:201], v[138:141], v[98:113]
	v_mfma_f32_32x32x16_bf16 v[66:81], v[198:201], v[156:159], v[66:81]
	v_mfma_f32_32x32x16_bf16 v[98:113], v[228:231], v[142:145], v[98:113]
	v_mfma_f32_32x32x16_bf16 v[66:81], v[228:231], v[160:163], v[66:81]
	s_barrier
	v_add3_u32 v246, v244, v240, s10
	v_add3_u32 v247, v244, v241, s10
	v_add3_u32 v248, v244, v242, s10
	v_add3_u32 v249, v244, v243, s10
	ds_read_b128 v[130:133], v246 offset:16384
	ds_read_b128 v[134:137], v247 offset:16384
	ds_read_b128 v[138:141], v248 offset:16384
	ds_read_b128 v[142:145], v249 offset:16384
	ds_read_b128 v[146:149], v246 offset:20480
	ds_read_b128 v[150:153], v247 offset:20480
	ds_read_b128 v[156:159], v248 offset:20480
	ds_read_b128 v[160:163], v249 offset:20480
	s_barrier
	s_waitcnt lgkmcnt(0)
	v_mfma_f32_32x32x16_bf16 v[50:65], v[170:173], v[130:133], v[50:65]
	v_mfma_f32_32x32x16_bf16 v[18:33], v[170:173], v[146:149], v[18:33]
	v_mfma_f32_32x32x16_bf16 v[50:65], v[174:177], v[134:137], v[50:65]
	v_mfma_f32_32x32x16_bf16 v[18:33], v[174:177], v[150:153], v[18:33]
	v_mfma_f32_32x32x16_bf16 v[50:65], v[178:181], v[138:141], v[50:65]
	v_mfma_f32_32x32x16_bf16 v[18:33], v[178:181], v[156:159], v[18:33]
	v_mfma_f32_32x32x16_bf16 v[50:65], v[186:189], v[142:145], v[50:65]
	v_mfma_f32_32x32x16_bf16 v[18:33], v[186:189], v[160:163], v[18:33]
	v_mfma_f32_32x32x16_bf16 v[34:49], v[190:193], v[130:133], v[34:49]
	v_mfma_f32_32x32x16_bf16 v[2:17], v[190:193], v[146:149], v[2:17]
	v_mfma_f32_32x32x16_bf16 v[34:49], v[194:197], v[134:137], v[34:49]
	v_mfma_f32_32x32x16_bf16 v[2:17], v[194:197], v[150:153], v[2:17]
	v_mfma_f32_32x32x16_bf16 v[34:49], v[198:201], v[138:141], v[34:49]
	v_mfma_f32_32x32x16_bf16 v[2:17], v[198:201], v[156:159], v[2:17]
	v_mfma_f32_32x32x16_bf16 v[34:49], v[228:231], v[142:145], v[34:49]
	v_mfma_f32_32x32x16_bf16 v[2:17], v[228:231], v[160:163], v[2:17]
	s_barrier
	s_cmp_eq_u32 s101, 0
	s_cbranch_scc0 .Lg8_qb_p1
	s_barrier

; template <bool SWAP>
; DI void gemm_mainloop(f32x16 (&acc)[4][2], const u16* __restrict__ A, int lda, int rlo, int rhi,
;                       const u16* __restrict__ B, int ldb, int K, char* lds, const u16* zero_line) {
;     ...
;   auto glds = [&](int kt, int st) {
;     char* as_ = lds + st * 65536 + tid * 16;
; #pragma unroll
;     for (int i = 0; i < 4; ++i) {
;       const int rr = lr + 64 * i;
;       const u16* srca = (rr >= rlo && rr < rhi) ? (ap + (ptrdiff_t)(64 * i) * lda + kt * 64) : (zero_line + lc * 8);
;       __builtin_amdgcn_global_load_lds((const unsigned*)srca, (lds_u32*)(as_ + i * 8192), 16, 0, 0);
;       __builtin_amdgcn_global_load_lds((const unsigned*)(bp + (ptrdiff_t)(64 * i) * ldb + kt * 64), (lds_u32*)(as_ + 32768 + i * 8192), 16, 0, 0);
;     }
;   };
;     ...
; #pragma unroll 2
;   for (int kt = 0; kt < nk; ++kt) {
;     const char* st = lds + (kt & 1) * 65536;
;     ldfrag(st, 0, 0);
;     mma(1);
;     pat_rd();
;     if (kt + 1 < nk) glds(kt + 1, (kt + 1) & 1);
;     ldfrag(st, 1, 1);
;     mma(0);
;     pat_rd();
;     ldfrag(st, 2, 0);
;     mma(1);
;     pat_rd();
;     ldfrag(st, 3, 1);
;     mma(0);
;     pat_rd();
;     asm volatile("s_waitcnt vmcnt(0)" ::: "memory");
;     __syncthreads();
.Lg8_ia:
	s_add_u32 m0, s100, 0x14000
	s_nop 0
	global_load_lds_dwordx4 v241, s[6:7]
	v_add_u32_e32 v241, 0x80, v241
	v_add3_u32 v187, v186, v161, 0
	v_add3_u32 v248, v186, v163, 0
	ds_read_b128 v[176:179], v187 offset:32768
	ds_read_b128 v[180:183], v248 offset:32768
	v_add3_u32 v187, v186, v164, 0
	v_add3_u32 v248, v186, v165, 0
	ds_read_b128 v[192:195], v187 offset:32768
	ds_read_b128 v[196:199], v248 offset:32768
	v_add3_u32 v187, v166, v161, 0
	v_add3_u32 v248, v166, v163, 0
	ds_read_b128 v[130:133], v187
	ds_read_b128 v[134:137], v248
	ds_read_b128 v[146:149], v187 offset:4096
	ds_read_b128 v[150:153], v248 offset:4096
	v_add3_u32 v187, v166, v164, 0
	v_add3_u32 v248, v166, v165, 0
	ds_read_b128 v[138:141], v187
	ds_read_b128 v[142:145], v248
	ds_read_b128 v[168:171], v187 offset:4096
	ds_read_b128 v[172:175], v248 offset:4096
	s_add_u32 m0, s100, 0x16000
	s_nop 0
	global_load_lds_dwordx4 v243, s[6:7]
	v_add_u32_e32 v243, 0x80, v243
	s_waitcnt lgkmcnt(8)
	s_barrier
	s_waitcnt lgkmcnt(0)
	v_mfma_f32_32x32x16_bf16 v[114:129], v[176:179], v[130:133], v[114:129]
	v_mfma_f32_32x32x16_bf16 v[98:113], v[176:179], v[146:149], v[98:113]
	v_mfma_f32_32x32x16_bf16 v[114:129], v[180:183], v[134:137], v[114:129]
	v_mfma_f32_32x32x16_bf16 v[98:113], v[180:183], v[150:153], v[98:113]
	v_mfma_f32_32x32x16_bf16 v[114:129], v[192:195], v[138:141], v[114:129]
	v_mfma_f32_32x32x16_bf16 v[98:113], v[192:195], v[168:171], v[98:113]
	v_mfma_f32_32x32x16_bf16 v[114:129], v[196:199], v[142:145], v[114:129]
	v_mfma_f32_32x32x16_bf16 v[98:113], v[196:199], v[172:175], v[98:113]
	s_barrier
	s_add_u32 m0, s100, 0x8000
	s_nop 0
	global_load_lds_dwordx4 v244, s[8:9]
	v_add_u32_e32 v244, 0x80, v244
	v_add3_u32 v187, v186, v161, 0
	v_add3_u32 v248, v186, v163, 0
	ds_read_b128 v[200:203], v187 offset:49152
	ds_read_b128 v[228:231], v248 offset:49152
	v_add3_u32 v187, v186, v164, 0
	v_add3_u32 v248, v186, v165, 0
	ds_read_b128 v[232:235], v187 offset:49152
	ds_read_b128 v[236:239], v248 offset:49152
	s_add_u32 m0, s100, 0xa000
	s_nop 0
	global_load_lds_dwordx4 v246, s[8:9]
	v_add_u32_e32 v246, 0x80, v246
	s_barrier
	s_waitcnt lgkmcnt(0)
	v_mfma_f32_32x32x16_bf16 v[82:97], v[200:203], v[130:133], v[82:97]
	v_mfma_f32_32x32x16_bf16 v[50:65], v[200:203], v[146:149], v[50:65]
	v_mfma_f32_32x32x16_bf16 v[82:97], v[228:231], v[134:137], v[82:97]
	v_mfma_f32_32x32x16_bf16 v[50:65], v[228:231], v[150:153], v[50:65]
	v_mfma_f32_32x32x16_bf16 v[82:97], v[232:235], v[138:141], v[82:97]
	v_mfma_f32_32x32x16_bf16 v[50:65], v[232:235], v[168:171], v[50:65]
	v_mfma_f32_32x32x16_bf16 v[82:97], v[236:239], v[142:145], v[82:97]
	v_mfma_f32_32x32x16_bf16 v[50:65], v[236:239], v[172:175], v[50:65]
	s_barrier
	s_add_u32 m0, s100, 0x0
	s_nop 0
	global_load_lds_dwordx4 v240, s[6:7]
	v_add_u32_e32 v240, 0x80, v240
	v_add3_u32 v187, v166, v161, 0
	v_add3_u32 v248, v166, v163, 0
	ds_read_b128 v[130:133], v187 offset:16384
	ds_read_b128 v[134:137], v248 offset:16384
	ds_read_b128 v[146:149], v187 offset:20480
	ds_read_b128 v[150:153], v248 offset:20480
	v_add3_u32 v187, v166, v164, 0
	v_add3_u32 v248, v166, v165, 0
	ds_read_b128 v[138:141], v187 offset:16384
	ds_read_b128 v[142:145], v248 offset:16384
	ds_read_b128 v[168:171], v187 offset:20480
	ds_read_b128 v[172:175], v248 offset:20480
	s_add_u32 m0, s100, 0x2000
	s_nop 0
	global_load_lds_dwordx4 v242, s[6:7]
	v_add_u32_e32 v242, 0x80, v242
	s_barrier
	s_waitcnt lgkmcnt(0)
	v_mfma_f32_32x32x16_bf16 v[66:81], v[176:179], v[130:133], v[66:81]
	v_mfma_f32_32x32x16_bf16 v[34:49], v[176:179], v[146:149], v[34:49]
	v_mfma_f32_32x32x16_bf16 v[66:81], v[180:183], v[134:137], v[66:81]
	v_mfma_f32_32x32x16_bf16 v[34:49], v[180:183], v[150:153], v[34:49]
	v_mfma_f32_32x32x16_bf16 v[66:81], v[192:195], v[138:141], v[66:81]
	v_mfma_f32_32x32x16_bf16 v[34:49], v[192:195], v[168:171], v[34:49]
	v_mfma_f32_32x32x16_bf16 v[66:81], v[196:199], v[142:145], v[66:81]
	v_mfma_f32_32x32x16_bf16 v[34:49], v[196:199], v[172:175], v[34:49]
	s_barrier
	s_add_u32 m0, s100, 0xc000
	s_nop 0
	global_load_lds_dwordx4 v245, s[8:9]
	v_add_u32_e32 v245, 0x80, v245
	s_add_u32 m0, s100, 0xe000
	s_nop 0
	global_load_lds_dwordx4 v247, s[8:9]
	v_add_u32_e32 v247, 0x80, v247
	s_waitcnt vmcnt(6)
	s_barrier
	v_mfma_f32_32x32x16_bf16 v[18:33], v[200:203], v[130:133], v[18:33]
	v_mfma_f32_32x32x16_bf16 v[2:17], v[200:203], v[146:149], v[2:17]
	v_mfma_f32_32x32x16_bf16 v[18:33], v[228:231], v[134:137], v[18:33]
	v_mfma_f32_32x32x16_bf16 v[2:17], v[228:231], v[150:153], v[2:17]
	v_mfma_f32_32x32x16_bf16 v[18:33], v[232:235], v[138:141], v[18:33]
	v_mfma_f32_32x32x16_bf16 v[2:17], v[232:235], v[168:171], v[2:17]
	v_mfma_f32_32x32x16_bf16 v[18:33], v[236:239], v[142:145], v[18:33]
	v_mfma_f32_32x32x16_bf16 v[2:17], v[236:239], v[172:175], v[2:17]
	s_barrier
	s_add_u32 m0, s100, 0x4000
	s_nop 0
	global_load_lds_dwordx4 v241, s[6:7]
	v_add_u32_e32 v241, 0x80, v241
	v_add3_u32 v187, v186, v161, s10
	v_add3_u32 v248, v186, v163, s10
	ds_read_b128 v[176:179], v187 offset:32768
	ds_read_b128 v[180:183], v248 offset:32768
	v_add3_u32 v187, v186, v164, s10
	v_add3_u32 v248, v186, v165, s10
	ds_read_b128 v[192:195], v187 offset:32768
	ds_read_b128 v[196:199], v248 offset:32768
	v_add3_u32 v187, v166, v161, s10
	v_add3_u32 v248, v166, v163, s10
	ds_read_b128 v[130:133], v187
	ds_read_b128 v[134:137], v248
	ds_read_b128 v[146:149], v187 offset:4096
	ds_read_b128 v[150:153], v248 offset:4096
	v_add3_u32 v187, v166, v164, s10
	v_add3_u32 v248, v166, v165, s10
	ds_read_b128 v[138:141], v187
	ds_read_b128 v[142:145], v248
	ds_read_b128 v[168:171], v187 offset:4096
	ds_read_b128 v[172:175], v248 offset:4096
	s_add_u32 m0, s100, 0x6000
	s_nop 0
	global_load_lds_dwordx4 v243, s[6:7]
	v_add_u32_e32 v243, 0x80, v243
	s_waitcnt lgkmcnt(8)
	s_barrier
; template <bool SWAP>
; DI void gemm_mainloop(f32x16 (&acc)[4][2], const u16* __restrict__ A, int lda, int rlo, int rhi,
;                       const u16* __restrict__ B, int ldb, int K, char* lds, const u16* zero_line) {
;     ...
; #pragma unroll 2
;   for (int kt = 0; kt < nk; ++kt) {
;     const char* st = lds + (kt & 1) * 65536;
;     ldfrag(st, 0, 0);
;     mma(1);
;     pat_rd();
;     if (kt + 1 < nk) glds(kt + 1, (kt + 1) & 1);
;     ldfrag(st, 1, 1);
;     mma(0);
;     pat_rd();
;     ldfrag(st, 2, 0);
;     mma(1);
;     pat_rd();
;     ldfrag(st, 3, 1);
;     mma(0);
;     pat_rd();
;     asm volatile("s_waitcnt vmcnt(0)" ::: "memory");
;     __syncthreads();
;   }
	s_waitcnt lgkmcnt(0)
	v_mfma_f32_32x32x16_bf16 v[114:129], v[176:179], v[130:133], v[114:129]
	v_mfma_f32_32x32x16_bf16 v[98:113], v[176:179], v[146:149], v[98:113]
	v_mfma_f32_32x32x16_bf16 v[114:129], v[180:183], v[134:137], v[114:129]
	v_mfma_f32_32x32x16_bf16 v[98:113], v[180:183], v[150:153], v[98:113]
	v_mfma_f32_32x32x16_bf16 v[114:129], v[192:195], v[138:141], v[114:129]
	v_mfma_f32_32x32x16_bf16 v[98:113], v[192:195], v[168:171], v[98:113]
	v_mfma_f32_32x32x16_bf16 v[114:129], v[196:199], v[142:145], v[114:129]
	v_mfma_f32_32x32x16_bf16 v[98:113], v[196:199], v[172:175], v[98:113]
	s_barrier
	s_add_u32 m0, s100, 0x18000
	s_nop 0
	global_load_lds_dwordx4 v244, s[8:9]
	v_add_u32_e32 v244, 0x80, v244
	v_add3_u32 v187, v186, v161, s10
	v_add3_u32 v248, v186, v163, s10
	ds_read_b128 v[200:203], v187 offset:49152
	ds_read_b128 v[228:231], v248 offset:49152
	v_add3_u32 v187, v186, v164, s10
	v_add3_u32 v248, v186, v165, s10
	ds_read_b128 v[232:235], v187 offset:49152
	ds_read_b128 v[236:239], v248 offset:49152
	s_add_u32 m0, s100, 0x1a000
	s_nop 0
	global_load_lds_dwordx4 v246, s[8:9]
	v_add_u32_e32 v246, 0x80, v246
	s_barrier
	s_waitcnt lgkmcnt(0)
	v_mfma_f32_32x32x16_bf16 v[82:97], v[200:203], v[130:133], v[82:97]
	v_mfma_f32_32x32x16_bf16 v[50:65], v[200:203], v[146:149], v[50:65]
	v_mfma_f32_32x32x16_bf16 v[82:97], v[228:231], v[134:137], v[82:97]
	v_mfma_f32_32x32x16_bf16 v[50:65], v[228:231], v[150:153], v[50:65]
	v_mfma_f32_32x32x16_bf16 v[82:97], v[232:235], v[138:141], v[82:97]
	v_mfma_f32_32x32x16_bf16 v[50:65], v[232:235], v[168:171], v[50:65]
	v_mfma_f32_32x32x16_bf16 v[82:97], v[236:239], v[142:145], v[82:97]
	v_mfma_f32_32x32x16_bf16 v[50:65], v[236:239], v[172:175], v[50:65]
	s_barrier
	s_add_u32 m0, s100, 0x10000
	s_nop 0
	global_load_lds_dwordx4 v240, s[6:7]
	v_add_u32_e32 v240, 0x80, v240
	v_add3_u32 v187, v166, v161, s10
	v_add3_u32 v248, v166, v163, s10
	ds_read_b128 v[130:133], v187 offset:16384
	ds_read_b128 v[134:137], v248 offset:16384
	ds_read_b128 v[146:149], v187 offset:20480
	ds_read_b128 v[150:153], v248 offset:20480
	v_add3_u32 v187, v166, v164, s10
	v_add3_u32 v248, v166, v165, s10
	ds_read_b128 v[138:141], v187 offset:16384
	ds_read_b128 v[142:145], v248 offset:16384
	ds_read_b128 v[168:171], v187 offset:20480
	ds_read_b128 v[172:175], v248 offset:20480
	s_add_u32 m0, s100, 0x12000
	s_nop 0
	global_load_lds_dwordx4 v242, s[6:7]
	v_add_u32_e32 v242, 0x80, v242
	s_barrier
	s_waitcnt lgkmcnt(0)
	v_mfma_f32_32x32x16_bf16 v[66:81], v[176:179], v[130:133], v[66:81]
	v_mfma_f32_32x32x16_bf16 v[34:49], v[176:179], v[146:149], v[34:49]
	v_mfma_f32_32x32x16_bf16 v[66:81], v[180:183], v[134:137], v[66:81]
	v_mfma_f32_32x32x16_bf16 v[34:49], v[180:183], v[150:153], v[34:49]
	v_mfma_f32_32x32x16_bf16 v[66:81], v[192:195], v[138:141], v[66:81]
	v_mfma_f32_32x32x16_bf16 v[34:49], v[192:195], v[168:171], v[34:49]
	v_mfma_f32_32x32x16_bf16 v[66:81], v[196:199], v[142:145], v[66:81]
	v_mfma_f32_32x32x16_bf16 v[34:49], v[196:199], v[172:175], v[34:49]
	s_barrier
	s_add_u32 m0, s100, 0x1c000
	s_nop 0
	global_load_lds_dwordx4 v245, s[8:9]
	v_add_u32_e32 v245, 0x80, v245
	s_add_u32 m0, s100, 0x1e000
	s_nop 0
	global_load_lds_dwordx4 v247, s[8:9]
	v_add_u32_e32 v247, 0x80, v247
	s_waitcnt vmcnt(6)
	s_barrier
	v_mfma_f32_32x32x16_bf16 v[18:33], v[200:203], v[130:133], v[18:33]
	v_mfma_f32_32x32x16_bf16 v[2:17], v[200:203], v[146:149], v[2:17]
	v_mfma_f32_32x32x16_bf16 v[18:33], v[228:231], v[134:137], v[18:33]
	v_mfma_f32_32x32x16_bf16 v[2:17], v[228:231], v[150:153], v[2:17]
	v_mfma_f32_32x32x16_bf16 v[18:33], v[232:235], v[138:141], v[18:33]
	v_mfma_f32_32x32x16_bf16 v[2:17], v[232:235], v[168:171], v[2:17]
	v_mfma_f32_32x32x16_bf16 v[18:33], v[236:239], v[142:145], v[18:33]
	v_mfma_f32_32x32x16_bf16 v[2:17], v[236:239], v[172:175], v[2:17]
	s_barrier
	s_add_i32 s11, s11, 2
	s_cmp_lt_u32 s11, 14
	s_cbranch_scc1 .Lg8_ia
	v_add3_u32 v187, v186, v161, 0
	v_add3_u32 v248, v186, v163, 0
	ds_read_b128 v[176:179], v187 offset:32768
	ds_read_b128 v[180:183], v248 offset:32768
	v_add3_u32 v187, v186, v164, 0
	v_add3_u32 v248, v186, v165, 0
	ds_read_b128 v[192:195], v187 offset:32768
	ds_read_b128 v[196:199], v248 offset:32768
	v_add3_u32 v187, v166, v161, 0
	v_add3_u32 v248, v166, v163, 0
	ds_read_b128 v[130:133], v187
	ds_read_b128 v[134:137], v248
	ds_read_b128 v[146:149], v187 offset:4096
	ds_read_b128 v[150:153], v248 offset:4096
	v_add3_u32 v187, v166, v164, 0
	v_add3_u32 v248, v166, v165, 0
	ds_read_b128 v[138:141], v187
	ds_read_b128 v[142:145], v248
	ds_read_b128 v[168:171], v187 offset:4096
	ds_read_b128 v[172:175], v248 offset:4096
	s_add_u32 m0, s100, 0x14000
	s_nop 0
	global_load_lds_dwordx4 v241, s[6:7]
	v_add_u32_e32 v241, 0x80, v241
	s_add_u32 m0, s100, 0x16000
	s_nop 0
	global_load_lds_dwordx4 v243, s[6:7]
	v_add_u32_e32 v243, 0x80, v243
	s_barrier
	s_waitcnt lgkmcnt(0)
	v_mfma_f32_32x32x16_bf16 v[114:129], v[176:179], v[130:133], v[114:129]
	v_mfma_f32_32x32x16_bf16 v[98:113], v[176:179], v[146:149], v[98:113]
	v_mfma_f32_32x32x16_bf16 v[114:129], v[180:183], v[134:137], v[114:129]
	v_mfma_f32_32x32x16_bf16 v[98:113], v[180:183], v[150:153], v[98:113]
	v_mfma_f32_32x32x16_bf16 v[114:129], v[192:195], v[138:141], v[114:129]
	v_mfma_f32_32x32x16_bf16 v[98:113], v[192:195], v[168:171], v[98:113]
	v_mfma_f32_32x32x16_bf16 v[114:129], v[196:199], v[142:145], v[114:129]
	v_mfma_f32_32x32x16_bf16 v[98:113], v[196:199], v[172:175], v[98:113]
	s_barrier
	v_add3_u32 v187, v186, v161, 0
	v_add3_u32 v248, v186, v163, 0
	ds_read_b128 v[200:203], v187 offset:49152
	ds_read_b128 v[228:231], v248 offset:49152
	v_add3_u32 v187, v186, v164, 0
	v_add3_u32 v248, v186, v165, 0
	ds_read_b128 v[232:235], v187 offset:49152
	ds_read_b128 v[236:239], v248 offset:49152
	s_barrier
; template <bool SWAP>
; DI void gemm_mainloop(f32x16 (&acc)[4][2], const u16* __restrict__ A, int lda, int rlo, int rhi,
;                       const u16* __restrict__ B, int ldb, int K, char* lds, const u16* zero_line) {
;     ...
; #pragma unroll 2
;   for (int kt = 0; kt < nk; ++kt) {
;     const char* st = lds + (kt & 1) * 65536;
;     ldfrag(st, 0, 0);
;     mma(1);
;     pat_rd();
;     if (kt + 1 < nk) glds(kt + 1, (kt + 1) & 1);
;     ldfrag(st, 1, 1);
;     mma(0);
;     pat_rd();
;     ldfrag(st, 2, 0);
;     mma(1);
;     pat_rd();
;     ldfrag(st, 3, 1);
;     mma(0);
;     pat_rd();
;     asm volatile("s_waitcnt vmcnt(0)" ::: "memory");
;     __syncthreads();
;   }
;   mma(1);
	s_waitcnt lgkmcnt(0)
	v_mfma_f32_32x32x16_bf16 v[82:97], v[200:203], v[130:133], v[82:97]
	v_mfma_f32_32x32x16_bf16 v[50:65], v[200:203], v[146:149], v[50:65]
	v_mfma_f32_32x32x16_bf16 v[82:97], v[228:231], v[134:137], v[82:97]
	v_mfma_f32_32x32x16_bf16 v[50:65], v[228:231], v[150:153], v[50:65]
	v_mfma_f32_32x32x16_bf16 v[82:97], v[232:235], v[138:141], v[82:97]
	v_mfma_f32_32x32x16_bf16 v[50:65], v[232:235], v[168:171], v[50:65]
	v_mfma_f32_32x32x16_bf16 v[82:97], v[236:239], v[142:145], v[82:97]
	v_mfma_f32_32x32x16_bf16 v[50:65], v[236:239], v[172:175], v[50:65]
	s_barrier
	v_add3_u32 v187, v166, v161, 0
	v_add3_u32 v248, v166, v163, 0
	ds_read_b128 v[130:133], v187 offset:16384
	ds_read_b128 v[134:137], v248 offset:16384
	ds_read_b128 v[146:149], v187 offset:20480
	ds_read_b128 v[150:153], v248 offset:20480
	v_add3_u32 v187, v166, v164, 0
	v_add3_u32 v248, v166, v165, 0
	ds_read_b128 v[138:141], v187 offset:16384
	ds_read_b128 v[142:145], v248 offset:16384
	ds_read_b128 v[168:171], v187 offset:20480
	ds_read_b128 v[172:175], v248 offset:20480
	s_waitcnt vmcnt(4)
	s_barrier
	s_waitcnt lgkmcnt(0)
	v_mfma_f32_32x32x16_bf16 v[66:81], v[176:179], v[130:133], v[66:81]
	v_mfma_f32_32x32x16_bf16 v[34:49], v[176:179], v[146:149], v[34:49]
	v_mfma_f32_32x32x16_bf16 v[66:81], v[180:183], v[134:137], v[66:81]
	v_mfma_f32_32x32x16_bf16 v[34:49], v[180:183], v[150:153], v[34:49]
	v_mfma_f32_32x32x16_bf16 v[66:81], v[192:195], v[138:141], v[66:81]
	v_mfma_f32_32x32x16_bf16 v[34:49], v[192:195], v[168:171], v[34:49]
	v_mfma_f32_32x32x16_bf16 v[66:81], v[196:199], v[142:145], v[66:81]
	v_mfma_f32_32x32x16_bf16 v[34:49], v[196:199], v[172:175], v[34:49]
	v_mfma_f32_32x32x16_bf16 v[18:33], v[200:203], v[130:133], v[18:33]
	v_mfma_f32_32x32x16_bf16 v[2:17], v[200:203], v[146:149], v[2:17]
	v_mfma_f32_32x32x16_bf16 v[18:33], v[228:231], v[134:137], v[18:33]
	v_mfma_f32_32x32x16_bf16 v[2:17], v[228:231], v[150:153], v[2:17]
	v_mfma_f32_32x32x16_bf16 v[18:33], v[232:235], v[138:141], v[18:33]
	v_mfma_f32_32x32x16_bf16 v[2:17], v[232:235], v[168:171], v[2:17]
	v_mfma_f32_32x32x16_bf16 v[18:33], v[236:239], v[142:145], v[18:33]
	v_mfma_f32_32x32x16_bf16 v[2:17], v[236:239], v[172:175], v[2:17]
	s_barrier
	v_add3_u32 v187, v186, v161, s10
	v_add3_u32 v248, v186, v163, s10
	ds_read_b128 v[176:179], v187 offset:32768
	ds_read_b128 v[180:183], v248 offset:32768
	v_add3_u32 v187, v186, v164, s10
	v_add3_u32 v248, v186, v165, s10
	ds_read_b128 v[192:195], v187 offset:32768
	ds_read_b128 v[196:199], v248 offset:32768
	v_add3_u32 v187, v166, v161, s10
	v_add3_u32 v248, v166, v163, s10
	ds_read_b128 v[130:133], v187
	ds_read_b128 v[134:137], v248
	ds_read_b128 v[146:149], v187 offset:4096
	ds_read_b128 v[150:153], v248 offset:4096
	v_add3_u32 v187, v166, v164, s10
	v_add3_u32 v248, v166, v165, s10
	ds_read_b128 v[138:141], v187
	ds_read_b128 v[142:145], v248
	ds_read_b128 v[168:171], v187 offset:4096
	ds_read_b128 v[172:175], v248 offset:4096
	s_waitcnt vmcnt(2)
	s_barrier
	s_waitcnt lgkmcnt(0)
	v_mfma_f32_32x32x16_bf16 v[114:129], v[176:179], v[130:133], v[114:129]
	v_mfma_f32_32x32x16_bf16 v[98:113], v[176:179], v[146:149], v[98:113]
	v_mfma_f32_32x32x16_bf16 v[114:129], v[180:183], v[134:137], v[114:129]
	v_mfma_f32_32x32x16_bf16 v[98:113], v[180:183], v[150:153], v[98:113]
	v_mfma_f32_32x32x16_bf16 v[114:129], v[192:195], v[138:141], v[114:129]
	v_mfma_f32_32x32x16_bf16 v[98:113], v[192:195], v[168:171], v[98:113]
	v_mfma_f32_32x32x16_bf16 v[114:129], v[196:199], v[142:145], v[114:129]
	v_mfma_f32_32x32x16_bf16 v[98:113], v[196:199], v[172:175], v[98:113]
	s_barrier
	v_add3_u32 v187, v186, v161, s10
	v_add3_u32 v248, v186, v163, s10
	ds_read_b128 v[200:203], v187 offset:49152
	ds_read_b128 v[228:231], v248 offset:49152
	v_add3_u32 v187, v186, v164, s10
	v_add3_u32 v248, v186, v165, s10
	ds_read_b128 v[232:235], v187 offset:49152
	ds_read_b128 v[236:239], v248 offset:49152
	s_waitcnt vmcnt(0)
	s_barrier
	s_waitcnt lgkmcnt(0)
	v_mfma_f32_32x32x16_bf16 v[82:97], v[200:203], v[130:133], v[82:97]
	v_mfma_f32_32x32x16_bf16 v[50:65], v[200:203], v[146:149], v[50:65]
	v_mfma_f32_32x32x16_bf16 v[82:97], v[228:231], v[134:137], v[82:97]
	v_mfma_f32_32x32x16_bf16 v[50:65], v[228:231], v[150:153], v[50:65]
	v_mfma_f32_32x32x16_bf16 v[82:97], v[232:235], v[138:141], v[82:97]
	v_mfma_f32_32x32x16_bf16 v[50:65], v[232:235], v[168:171], v[50:65]
	v_mfma_f32_32x32x16_bf16 v[82:97], v[236:239], v[142:145], v[82:97]
	v_mfma_f32_32x32x16_bf16 v[50:65], v[236:239], v[172:175], v[50:65]
	s_barrier
	v_add3_u32 v187, v166, v161, s10
	v_add3_u32 v248, v166, v163, s10
	ds_read_b128 v[130:133], v187 offset:16384
	ds_read_b128 v[134:137], v248 offset:16384
	ds_read_b128 v[146:149], v187 offset:20480
	ds_read_b128 v[150:153], v248 offset:20480
	v_add3_u32 v187, v166, v164, s10
	v_add3_u32 v248, v166, v165, s10
	ds_read_b128 v[138:141], v187 offset:16384
	ds_read_b128 v[142:145], v248 offset:16384
	ds_read_b128 v[168:171], v187 offset:20480
	ds_read_b128 v[172:175], v248 offset:20480
	s_barrier
	s_waitcnt lgkmcnt(0)
	v_mfma_f32_32x32x16_bf16 v[66:81], v[176:179], v[130:133], v[66:81]
	v_mfma_f32_32x32x16_bf16 v[34:49], v[176:179], v[146:149], v[34:49]
	v_mfma_f32_32x32x16_bf16 v[66:81], v[180:183], v[134:137], v[66:81]
	v_mfma_f32_32x32x16_bf16 v[34:49], v[180:183], v[150:153], v[34:49]
	v_mfma_f32_32x32x16_bf16 v[66:81], v[192:195], v[138:141], v[66:81]
	v_mfma_f32_32x32x16_bf16 v[34:49], v[192:195], v[168:171], v[34:49]
	v_mfma_f32_32x32x16_bf16 v[66:81], v[196:199], v[142:145], v[66:81]
	v_mfma_f32_32x32x16_bf16 v[34:49], v[196:199], v[172:175], v[34:49]
	v_mfma_f32_32x32x16_bf16 v[18:33], v[200:203], v[130:133], v[18:33]
	v_mfma_f32_32x32x16_bf16 v[2:17], v[200:203], v[146:149], v[2:17]
	v_mfma_f32_32x32x16_bf16 v[18:33], v[228:231], v[134:137], v[18:33]
	v_mfma_f32_32x32x16_bf16 v[2:17], v[228:231], v[150:153], v[2:17]
	v_mfma_f32_32x32x16_bf16 v[18:33], v[232:235], v[138:141], v[18:33]
	v_mfma_f32_32x32x16_bf16 v[2:17], v[232:235], v[168:171], v[2:17]
	v_mfma_f32_32x32x16_bf16 v[18:33], v[236:239], v[142:145], v[18:33]
	v_mfma_f32_32x32x16_bf16 v[2:17], v[236:239], v[172:175], v[2:17]
	s_barrier
	s_cmp_eq_u32 s101, 0
	s_cbranch_scc0 .Lg8_ia_p1
	s_barrier

; template <bool SWAP>
; DI void gemm_mainloop(f32x16 (&acc)[4][2], const u16* __restrict__ A, int lda, int rlo, int rhi,
;                       const u16* __restrict__ B, int ldb, int K, char* lds, const u16* zero_line) {
;     ...
;   auto glds = [&](int kt, int st) {
;     char* as_ = lds + st * 65536 + tid * 16;
; #pragma unroll
;     for (int i = 0; i < 4; ++i) {
;       const int rr = lr + 64 * i;
;       const u16* srca = (rr >= rlo && rr < rhi) ? (ap + (ptrdiff_t)(64 * i) * lda + kt * 64) : (zero_line + lc * 8);
;       __builtin_amdgcn_global_load_lds((const unsigned*)srca, (lds_u32*)(as_ + i * 8192), 16, 0, 0);
;       __builtin_amdgcn_global_load_lds((const unsigned*)(bp + (ptrdiff_t)(64 * i) * ldb + kt * 64), (lds_u32*)(as_ + 32768 + i * 8192), 16, 0, 0);
;     }
;   };
;     ...
; #pragma unroll 2
;   for (int kt = 0; kt < nk; ++kt) {
;     const char* st = lds + (kt & 1) * 65536;
;     ldfrag(st, 0, 0);
;     mma(1);
;     pat_rd();
;     if (kt + 1 < nk) glds(kt + 1, (kt + 1) & 1);
;     ldfrag(st, 1, 1);
;     mma(0);
;     pat_rd();
;     ldfrag(st, 2, 0);
;     mma(1);
;     pat_rd();
;     ldfrag(st, 3, 1);
;     mma(0);
;     pat_rd();
;     asm volatile("s_waitcnt vmcnt(0)" ::: "memory");
;     __syncthreads();
.Lg8_ib:
	s_add_u32 m0, s100, 0x14000
	s_nop 0
	global_load_lds_dwordx4 v241, s[6:7]
	v_add_u32_e32 v241, 0x80, v241
	v_add3_u32 v187, v186, v161, 0
	v_add3_u32 v248, v186, v163, 0
	ds_read_b128 v[176:179], v187 offset:32768
	ds_read_b128 v[180:183], v248 offset:32768
	v_add3_u32 v187, v186, v164, 0
	v_add3_u32 v248, v186, v165, 0
	ds_read_b128 v[192:195], v187 offset:32768
	ds_read_b128 v[196:199], v248 offset:32768
	v_add3_u32 v187, v166, v161, 0
	v_add3_u32 v248, v166, v163, 0
	ds_read_b128 v[130:133], v187
	ds_read_b128 v[134:137], v248
	ds_read_b128 v[146:149], v187 offset:4096
	ds_read_b128 v[150:153], v248 offset:4096
	v_add3_u32 v187, v166, v164, 0
	v_add3_u32 v248, v166, v165, 0
	ds_read_b128 v[138:141], v187
	ds_read_b128 v[142:145], v248
	ds_read_b128 v[168:171], v187 offset:4096
	ds_read_b128 v[172:175], v248 offset:4096
	s_add_u32 m0, s100, 0x16000
	s_nop 0
	global_load_lds_dwordx4 v243, s[6:7]
	v_add_u32_e32 v243, 0x80, v243
	s_waitcnt lgkmcnt(8)
	s_barrier
	s_waitcnt lgkmcnt(0)
	v_mfma_f32_32x32x16_bf16 v[114:129], v[130:133], v[176:179], v[114:129]
	v_mfma_f32_32x32x16_bf16 v[98:113], v[146:149], v[176:179], v[98:113]
	v_mfma_f32_32x32x16_bf16 v[114:129], v[134:137], v[180:183], v[114:129]
	v_mfma_f32_32x32x16_bf16 v[98:113], v[150:153], v[180:183], v[98:113]
	v_mfma_f32_32x32x16_bf16 v[114:129], v[138:141], v[192:195], v[114:129]
	v_mfma_f32_32x32x16_bf16 v[98:113], v[168:171], v[192:195], v[98:113]
	v_mfma_f32_32x32x16_bf16 v[114:129], v[142:145], v[196:199], v[114:129]
	v_mfma_f32_32x32x16_bf16 v[98:113], v[172:175], v[196:199], v[98:113]
	s_barrier
	s_add_u32 m0, s100, 0x8000
	s_nop 0
	global_load_lds_dwordx4 v244, s[8:9]
	v_add_u32_e32 v244, 0x80, v244
	v_add3_u32 v187, v186, v161, 0
	v_add3_u32 v248, v186, v163, 0
	ds_read_b128 v[200:203], v187 offset:49152
	ds_read_b128 v[228:231], v248 offset:49152
	v_add3_u32 v187, v186, v164, 0
	v_add3_u32 v248, v186, v165, 0
	ds_read_b128 v[232:235], v187 offset:49152
	ds_read_b128 v[236:239], v248 offset:49152
	s_add_u32 m0, s100, 0xa000
	s_nop 0
	global_load_lds_dwordx4 v246, s[8:9]
	v_add_u32_e32 v246, 0x80, v246
	s_barrier
	s_waitcnt lgkmcnt(0)
	v_mfma_f32_32x32x16_bf16 v[82:97], v[130:133], v[200:203], v[82:97]
	v_mfma_f32_32x32x16_bf16 v[50:65], v[146:149], v[200:203], v[50:65]
	v_mfma_f32_32x32x16_bf16 v[82:97], v[134:137], v[228:231], v[82:97]
	v_mfma_f32_32x32x16_bf16 v[50:65], v[150:153], v[228:231], v[50:65]
	v_mfma_f32_32x32x16_bf16 v[82:97], v[138:141], v[232:235], v[82:97]
	v_mfma_f32_32x32x16_bf16 v[50:65], v[168:171], v[232:235], v[50:65]
	v_mfma_f32_32x32x16_bf16 v[82:97], v[142:145], v[236:239], v[82:97]
	v_mfma_f32_32x32x16_bf16 v[50:65], v[172:175], v[236:239], v[50:65]
	s_barrier
	s_add_u32 m0, s100, 0x0
	s_nop 0
	global_load_lds_dwordx4 v240, s[6:7]
	v_add_u32_e32 v240, 0x80, v240
	v_add3_u32 v187, v166, v161, 0
	v_add3_u32 v248, v166, v163, 0
	ds_read_b128 v[130:133], v187 offset:16384
	ds_read_b128 v[134:137], v248 offset:16384
	ds_read_b128 v[146:149], v187 offset:20480
	ds_read_b128 v[150:153], v248 offset:20480
	v_add3_u32 v187, v166, v164, 0
	v_add3_u32 v248, v166, v165, 0
	ds_read_b128 v[138:141], v187 offset:16384
	ds_read_b128 v[142:145], v248 offset:16384
	ds_read_b128 v[168:171], v187 offset:20480
	ds_read_b128 v[172:175], v248 offset:20480
	s_add_u32 m0, s100, 0x2000
	s_nop 0
	global_load_lds_dwordx4 v242, s[6:7]
	v_add_u32_e32 v242, 0x80, v242
	s_barrier
	s_waitcnt lgkmcnt(0)
	v_mfma_f32_32x32x16_bf16 v[66:81], v[130:133], v[176:179], v[66:81]
	v_mfma_f32_32x32x16_bf16 v[34:49], v[146:149], v[176:179], v[34:49]
	v_mfma_f32_32x32x16_bf16 v[66:81], v[134:137], v[180:183], v[66:81]
	v_mfma_f32_32x32x16_bf16 v[34:49], v[150:153], v[180:183], v[34:49]
	v_mfma_f32_32x32x16_bf16 v[66:81], v[138:141], v[192:195], v[66:81]
	v_mfma_f32_32x32x16_bf16 v[34:49], v[168:171], v[192:195], v[34:49]
	v_mfma_f32_32x32x16_bf16 v[66:81], v[142:145], v[196:199], v[66:81]
	v_mfma_f32_32x32x16_bf16 v[34:49], v[172:175], v[196:199], v[34:49]
	s_barrier
	s_add_u32 m0, s100, 0xc000
	s_nop 0
	global_load_lds_dwordx4 v245, s[8:9]
	v_add_u32_e32 v245, 0x80, v245
	s_add_u32 m0, s100, 0xe000
	s_nop 0
	global_load_lds_dwordx4 v247, s[8:9]
	v_add_u32_e32 v247, 0x80, v247
	s_waitcnt vmcnt(6)
	s_barrier
	v_mfma_f32_32x32x16_bf16 v[18:33], v[130:133], v[200:203], v[18:33]
	v_mfma_f32_32x32x16_bf16 v[2:17], v[146:149], v[200:203], v[2:17]
	v_mfma_f32_32x32x16_bf16 v[18:33], v[134:137], v[228:231], v[18:33]
	v_mfma_f32_32x32x16_bf16 v[2:17], v[150:153], v[228:231], v[2:17]
	v_mfma_f32_32x32x16_bf16 v[18:33], v[138:141], v[232:235], v[18:33]
	v_mfma_f32_32x32x16_bf16 v[2:17], v[168:171], v[232:235], v[2:17]
	v_mfma_f32_32x32x16_bf16 v[18:33], v[142:145], v[236:239], v[18:33]
	v_mfma_f32_32x32x16_bf16 v[2:17], v[172:175], v[236:239], v[2:17]
	s_barrier
	s_add_u32 m0, s100, 0x4000
	s_nop 0
	global_load_lds_dwordx4 v241, s[6:7]
	v_add_u32_e32 v241, 0x80, v241
	v_add3_u32 v187, v186, v161, s10
	v_add3_u32 v248, v186, v163, s10
	ds_read_b128 v[176:179], v187 offset:32768
	ds_read_b128 v[180:183], v248 offset:32768
	v_add3_u32 v187, v186, v164, s10
	v_add3_u32 v248, v186, v165, s10
	ds_read_b128 v[192:195], v187 offset:32768
	ds_read_b128 v[196:199], v248 offset:32768
	v_add3_u32 v187, v166, v161, s10
	v_add3_u32 v248, v166, v163, s10
	ds_read_b128 v[130:133], v187
	ds_read_b128 v[134:137], v248
	ds_read_b128 v[146:149], v187 offset:4096
	ds_read_b128 v[150:153], v248 offset:4096
	v_add3_u32 v187, v166, v164, s10
	v_add3_u32 v248, v166, v165, s10
	ds_read_b128 v[138:141], v187
	ds_read_b128 v[142:145], v248
	ds_read_b128 v[168:171], v187 offset:4096
	ds_read_b128 v[172:175], v248 offset:4096
	s_add_u32 m0, s100, 0x6000
	s_nop 0
	global_load_lds_dwordx4 v243, s[6:7]
	v_add_u32_e32 v243, 0x80, v243
	s_waitcnt lgkmcnt(8)
	s_barrier
; template <bool SWAP>
; DI void gemm_mainloop(f32x16 (&acc)[4][2], const u16* __restrict__ A, int lda, int rlo, int rhi,
;                       const u16* __restrict__ B, int ldb, int K, char* lds, const u16* zero_line) {
;     ...
; #pragma unroll 2
;   for (int kt = 0; kt < nk; ++kt) {
;     const char* st = lds + (kt & 1) * 65536;
;     ldfrag(st, 0, 0);
;     mma(1);
;     pat_rd();
;     if (kt + 1 < nk) glds(kt + 1, (kt + 1) & 1);
;     ldfrag(st, 1, 1);
;     mma(0);
;     pat_rd();
;     ldfrag(st, 2, 0);
;     mma(1);
;     pat_rd();
;     ldfrag(st, 3, 1);
;     mma(0);
;     pat_rd();
;     asm volatile("s_waitcnt vmcnt(0)" ::: "memory");
;     __syncthreads();
;   }
	s_waitcnt lgkmcnt(0)
	v_mfma_f32_32x32x16_bf16 v[114:129], v[130:133], v[176:179], v[114:129]
	v_mfma_f32_32x32x16_bf16 v[98:113], v[146:149], v[176:179], v[98:113]
	v_mfma_f32_32x32x16_bf16 v[114:129], v[134:137], v[180:183], v[114:129]
	v_mfma_f32_32x32x16_bf16 v[98:113], v[150:153], v[180:183], v[98:113]
	v_mfma_f32_32x32x16_bf16 v[114:129], v[138:141], v[192:195], v[114:129]
	v_mfma_f32_32x32x16_bf16 v[98:113], v[168:171], v[192:195], v[98:113]
	v_mfma_f32_32x32x16_bf16 v[114:129], v[142:145], v[196:199], v[114:129]
	v_mfma_f32_32x32x16_bf16 v[98:113], v[172:175], v[196:199], v[98:113]
	s_barrier
	s_add_u32 m0, s100, 0x18000
	s_nop 0
	global_load_lds_dwordx4 v244, s[8:9]
	v_add_u32_e32 v244, 0x80, v244
	v_add3_u32 v187, v186, v161, s10
	v_add3_u32 v248, v186, v163, s10
	ds_read_b128 v[200:203], v187 offset:49152
	ds_read_b128 v[228:231], v248 offset:49152
	v_add3_u32 v187, v186, v164, s10
	v_add3_u32 v248, v186, v165, s10
	ds_read_b128 v[232:235], v187 offset:49152
	ds_read_b128 v[236:239], v248 offset:49152
	s_add_u32 m0, s100, 0x1a000
	s_nop 0
	global_load_lds_dwordx4 v246, s[8:9]
	v_add_u32_e32 v246, 0x80, v246
	s_barrier
	s_waitcnt lgkmcnt(0)
	v_mfma_f32_32x32x16_bf16 v[82:97], v[130:133], v[200:203], v[82:97]
	v_mfma_f32_32x32x16_bf16 v[50:65], v[146:149], v[200:203], v[50:65]
	v_mfma_f32_32x32x16_bf16 v[82:97], v[134:137], v[228:231], v[82:97]
	v_mfma_f32_32x32x16_bf16 v[50:65], v[150:153], v[228:231], v[50:65]
	v_mfma_f32_32x32x16_bf16 v[82:97], v[138:141], v[232:235], v[82:97]
	v_mfma_f32_32x32x16_bf16 v[50:65], v[168:171], v[232:235], v[50:65]
	v_mfma_f32_32x32x16_bf16 v[82:97], v[142:145], v[236:239], v[82:97]
	v_mfma_f32_32x32x16_bf16 v[50:65], v[172:175], v[236:239], v[50:65]
	s_barrier
	s_add_u32 m0, s100, 0x10000
	s_nop 0
	global_load_lds_dwordx4 v240, s[6:7]
	v_add_u32_e32 v240, 0x80, v240
	v_add3_u32 v187, v166, v161, s10
	v_add3_u32 v248, v166, v163, s10
	ds_read_b128 v[130:133], v187 offset:16384
	ds_read_b128 v[134:137], v248 offset:16384
	ds_read_b128 v[146:149], v187 offset:20480
	ds_read_b128 v[150:153], v248 offset:20480
	v_add3_u32 v187, v166, v164, s10
	v_add3_u32 v248, v166, v165, s10
	ds_read_b128 v[138:141], v187 offset:16384
	ds_read_b128 v[142:145], v248 offset:16384
	ds_read_b128 v[168:171], v187 offset:20480
	ds_read_b128 v[172:175], v248 offset:20480
	s_add_u32 m0, s100, 0x12000
	s_nop 0
	global_load_lds_dwordx4 v242, s[6:7]
	v_add_u32_e32 v242, 0x80, v242
	s_barrier
	s_waitcnt lgkmcnt(0)
	v_mfma_f32_32x32x16_bf16 v[66:81], v[130:133], v[176:179], v[66:81]
	v_mfma_f32_32x32x16_bf16 v[34:49], v[146:149], v[176:179], v[34:49]
	v_mfma_f32_32x32x16_bf16 v[66:81], v[134:137], v[180:183], v[66:81]
	v_mfma_f32_32x32x16_bf16 v[34:49], v[150:153], v[180:183], v[34:49]
	v_mfma_f32_32x32x16_bf16 v[66:81], v[138:141], v[192:195], v[66:81]
	v_mfma_f32_32x32x16_bf16 v[34:49], v[168:171], v[192:195], v[34:49]
	v_mfma_f32_32x32x16_bf16 v[66:81], v[142:145], v[196:199], v[66:81]
	v_mfma_f32_32x32x16_bf16 v[34:49], v[172:175], v[196:199], v[34:49]
	s_barrier
	s_add_u32 m0, s100, 0x1c000
	s_nop 0
	global_load_lds_dwordx4 v245, s[8:9]
	v_add_u32_e32 v245, 0x80, v245
	s_add_u32 m0, s100, 0x1e000
	s_nop 0
	global_load_lds_dwordx4 v247, s[8:9]
	v_add_u32_e32 v247, 0x80, v247
	s_waitcnt vmcnt(6)
	s_barrier
	v_mfma_f32_32x32x16_bf16 v[18:33], v[130:133], v[200:203], v[18:33]
	v_mfma_f32_32x32x16_bf16 v[2:17], v[146:149], v[200:203], v[2:17]
	v_mfma_f32_32x32x16_bf16 v[18:33], v[134:137], v[228:231], v[18:33]
	v_mfma_f32_32x32x16_bf16 v[2:17], v[150:153], v[228:231], v[2:17]
	v_mfma_f32_32x32x16_bf16 v[18:33], v[138:141], v[232:235], v[18:33]
	v_mfma_f32_32x32x16_bf16 v[2:17], v[168:171], v[232:235], v[2:17]
	v_mfma_f32_32x32x16_bf16 v[18:33], v[142:145], v[236:239], v[18:33]
	v_mfma_f32_32x32x16_bf16 v[2:17], v[172:175], v[236:239], v[2:17]
	s_barrier
	s_add_i32 s11, s11, 2
	s_cmp_lt_u32 s11, 14
	s_cbranch_scc1 .Lg8_ib
	v_add3_u32 v187, v186, v161, 0
	v_add3_u32 v248, v186, v163, 0
	ds_read_b128 v[176:179], v187 offset:32768
	ds_read_b128 v[180:183], v248 offset:32768
	v_add3_u32 v187, v186, v164, 0
	v_add3_u32 v248, v186, v165, 0
	ds_read_b128 v[192:195], v187 offset:32768
	ds_read_b128 v[196:199], v248 offset:32768
	v_add3_u32 v187, v166, v161, 0
	v_add3_u32 v248, v166, v163, 0
	ds_read_b128 v[130:133], v187
	ds_read_b128 v[134:137], v248
	ds_read_b128 v[146:149], v187 offset:4096
	ds_read_b128 v[150:153], v248 offset:4096
	v_add3_u32 v187, v166, v164, 0
	v_add3_u32 v248, v166, v165, 0
	ds_read_b128 v[138:141], v187
	ds_read_b128 v[142:145], v248
	ds_read_b128 v[168:171], v187 offset:4096
	ds_read_b128 v[172:175], v248 offset:4096
	s_add_u32 m0, s100, 0x14000
	s_nop 0
	global_load_lds_dwordx4 v241, s[6:7]
	v_add_u32_e32 v241, 0x80, v241
	s_add_u32 m0, s100, 0x16000
	s_nop 0
	global_load_lds_dwordx4 v243, s[6:7]
	v_add_u32_e32 v243, 0x80, v243
	s_barrier
	s_waitcnt lgkmcnt(0)
	v_mfma_f32_32x32x16_bf16 v[114:129], v[130:133], v[176:179], v[114:129]
	v_mfma_f32_32x32x16_bf16 v[98:113], v[146:149], v[176:179], v[98:113]
	v_mfma_f32_32x32x16_bf16 v[114:129], v[134:137], v[180:183], v[114:129]
	v_mfma_f32_32x32x16_bf16 v[98:113], v[150:153], v[180:183], v[98:113]
	v_mfma_f32_32x32x16_bf16 v[114:129], v[138:141], v[192:195], v[114:129]
	v_mfma_f32_32x32x16_bf16 v[98:113], v[168:171], v[192:195], v[98:113]
	v_mfma_f32_32x32x16_bf16 v[114:129], v[142:145], v[196:199], v[114:129]
	v_mfma_f32_32x32x16_bf16 v[98:113], v[172:175], v[196:199], v[98:113]
	s_barrier
	v_add3_u32 v187, v186, v161, 0
	v_add3_u32 v248, v186, v163, 0
	ds_read_b128 v[200:203], v187 offset:49152
	ds_read_b128 v[228:231], v248 offset:49152
	v_add3_u32 v187, v186, v164, 0
	v_add3_u32 v248, v186, v165, 0
	ds_read_b128 v[232:235], v187 offset:49152
	ds_read_b128 v[236:239], v248 offset:49152
	s_barrier
; template <bool SWAP>
; DI void gemm_mainloop(f32x16 (&acc)[4][2], const u16* __restrict__ A, int lda, int rlo, int rhi,
;                       const u16* __restrict__ B, int ldb, int K, char* lds, const u16* zero_line) {
;     ...
; #pragma unroll 2
;   for (int kt = 0; kt < nk; ++kt) {
;     const char* st = lds + (kt & 1) * 65536;
;     ldfrag(st, 0, 0);
;     mma(1);
;     pat_rd();
;     if (kt + 1 < nk) glds(kt + 1, (kt + 1) & 1);
;     ldfrag(st, 1, 1);
;     mma(0);
;     pat_rd();
;     ldfrag(st, 2, 0);
;     mma(1);
;     pat_rd();
;     ldfrag(st, 3, 1);
;     mma(0);
;     pat_rd();
;     asm volatile("s_waitcnt vmcnt(0)" ::: "memory");
;     __syncthreads();
;   }
;   mma(1);
	s_waitcnt lgkmcnt(0)
	v_mfma_f32_32x32x16_bf16 v[82:97], v[130:133], v[200:203], v[82:97]
	v_mfma_f32_32x32x16_bf16 v[50:65], v[146:149], v[200:203], v[50:65]
	v_mfma_f32_32x32x16_bf16 v[82:97], v[134:137], v[228:231], v[82:97]
	v_mfma_f32_32x32x16_bf16 v[50:65], v[150:153], v[228:231], v[50:65]
	v_mfma_f32_32x32x16_bf16 v[82:97], v[138:141], v[232:235], v[82:97]
	v_mfma_f32_32x32x16_bf16 v[50:65], v[168:171], v[232:235], v[50:65]
	v_mfma_f32_32x32x16_bf16 v[82:97], v[142:145], v[236:239], v[82:97]
	v_mfma_f32_32x32x16_bf16 v[50:65], v[172:175], v[236:239], v[50:65]
	s_barrier
	v_add3_u32 v187, v166, v161, 0
	v_add3_u32 v248, v166, v163, 0
	ds_read_b128 v[130:133], v187 offset:16384
	ds_read_b128 v[134:137], v248 offset:16384
	ds_read_b128 v[146:149], v187 offset:20480
	ds_read_b128 v[150:153], v248 offset:20480
	v_add3_u32 v187, v166, v164, 0
	v_add3_u32 v248, v166, v165, 0
	ds_read_b128 v[138:141], v187 offset:16384
	ds_read_b128 v[142:145], v248 offset:16384
	ds_read_b128 v[168:171], v187 offset:20480
	ds_read_b128 v[172:175], v248 offset:20480
	s_waitcnt vmcnt(4)
	s_barrier
	s_waitcnt lgkmcnt(0)
	v_mfma_f32_32x32x16_bf16 v[66:81], v[130:133], v[176:179], v[66:81]
	v_mfma_f32_32x32x16_bf16 v[34:49], v[146:149], v[176:179], v[34:49]
	v_mfma_f32_32x32x16_bf16 v[66:81], v[134:137], v[180:183], v[66:81]
	v_mfma_f32_32x32x16_bf16 v[34:49], v[150:153], v[180:183], v[34:49]
	v_mfma_f32_32x32x16_bf16 v[66:81], v[138:141], v[192:195], v[66:81]
	v_mfma_f32_32x32x16_bf16 v[34:49], v[168:171], v[192:195], v[34:49]
	v_mfma_f32_32x32x16_bf16 v[66:81], v[142:145], v[196:199], v[66:81]
	v_mfma_f32_32x32x16_bf16 v[34:49], v[172:175], v[196:199], v[34:49]
	v_mfma_f32_32x32x16_bf16 v[18:33], v[130:133], v[200:203], v[18:33]
	v_mfma_f32_32x32x16_bf16 v[2:17], v[146:149], v[200:203], v[2:17]
	v_mfma_f32_32x32x16_bf16 v[18:33], v[134:137], v[228:231], v[18:33]
	v_mfma_f32_32x32x16_bf16 v[2:17], v[150:153], v[228:231], v[2:17]
	v_mfma_f32_32x32x16_bf16 v[18:33], v[138:141], v[232:235], v[18:33]
	v_mfma_f32_32x32x16_bf16 v[2:17], v[168:171], v[232:235], v[2:17]
	v_mfma_f32_32x32x16_bf16 v[18:33], v[142:145], v[236:239], v[18:33]
	v_mfma_f32_32x32x16_bf16 v[2:17], v[172:175], v[236:239], v[2:17]
	s_barrier
	v_add3_u32 v187, v186, v161, s10
	v_add3_u32 v248, v186, v163, s10
	ds_read_b128 v[176:179], v187 offset:32768
	ds_read_b128 v[180:183], v248 offset:32768
	v_add3_u32 v187, v186, v164, s10
	v_add3_u32 v248, v186, v165, s10
	ds_read_b128 v[192:195], v187 offset:32768
	ds_read_b128 v[196:199], v248 offset:32768
	v_add3_u32 v187, v166, v161, s10
	v_add3_u32 v248, v166, v163, s10
	ds_read_b128 v[130:133], v187
	ds_read_b128 v[134:137], v248
	ds_read_b128 v[146:149], v187 offset:4096
	ds_read_b128 v[150:153], v248 offset:4096
	v_add3_u32 v187, v166, v164, s10
	v_add3_u32 v248, v166, v165, s10
	ds_read_b128 v[138:141], v187
	ds_read_b128 v[142:145], v248
	ds_read_b128 v[168:171], v187 offset:4096
	ds_read_b128 v[172:175], v248 offset:4096
	s_waitcnt vmcnt(2)
	s_barrier
	s_waitcnt lgkmcnt(0)
	v_mfma_f32_32x32x16_bf16 v[114:129], v[130:133], v[176:179], v[114:129]
	v_mfma_f32_32x32x16_bf16 v[98:113], v[146:149], v[176:179], v[98:113]
	v_mfma_f32_32x32x16_bf16 v[114:129], v[134:137], v[180:183], v[114:129]
	v_mfma_f32_32x32x16_bf16 v[98:113], v[150:153], v[180:183], v[98:113]
	v_mfma_f32_32x32x16_bf16 v[114:129], v[138:141], v[192:195], v[114:129]
	v_mfma_f32_32x32x16_bf16 v[98:113], v[168:171], v[192:195], v[98:113]
	v_mfma_f32_32x32x16_bf16 v[114:129], v[142:145], v[196:199], v[114:129]
	v_mfma_f32_32x32x16_bf16 v[98:113], v[172:175], v[196:199], v[98:113]
	s_barrier
	v_add3_u32 v187, v186, v161, s10
	v_add3_u32 v248, v186, v163, s10
	ds_read_b128 v[200:203], v187 offset:49152
	ds_read_b128 v[228:231], v248 offset:49152
	v_add3_u32 v187, v186, v164, s10
	v_add3_u32 v248, v186, v165, s10
	ds_read_b128 v[232:235], v187 offset:49152
	ds_read_b128 v[236:239], v248 offset:49152
	s_waitcnt vmcnt(0)
	s_barrier
	s_waitcnt lgkmcnt(0)
	v_mfma_f32_32x32x16_bf16 v[82:97], v[130:133], v[200:203], v[82:97]
	v_mfma_f32_32x32x16_bf16 v[50:65], v[146:149], v[200:203], v[50:65]
	v_mfma_f32_32x32x16_bf16 v[82:97], v[134:137], v[228:231], v[82:97]
	v_mfma_f32_32x32x16_bf16 v[50:65], v[150:153], v[228:231], v[50:65]
	v_mfma_f32_32x32x16_bf16 v[82:97], v[138:141], v[232:235], v[82:97]
	v_mfma_f32_32x32x16_bf16 v[50:65], v[168:171], v[232:235], v[50:65]
	v_mfma_f32_32x32x16_bf16 v[82:97], v[142:145], v[236:239], v[82:97]
	v_mfma_f32_32x32x16_bf16 v[50:65], v[172:175], v[236:239], v[50:65]
	s_barrier
	v_add3_u32 v187, v166, v161, s10
	v_add3_u32 v248, v166, v163, s10
	ds_read_b128 v[130:133], v187 offset:16384
	ds_read_b128 v[134:137], v248 offset:16384
	ds_read_b128 v[146:149], v187 offset:20480
	ds_read_b128 v[150:153], v248 offset:20480
	v_add3_u32 v187, v166, v164, s10
	v_add3_u32 v248, v166, v165, s10
	ds_read_b128 v[138:141], v187 offset:16384
	ds_read_b128 v[142:145], v248 offset:16384
	ds_read_b128 v[168:171], v187 offset:20480
	ds_read_b128 v[172:175], v248 offset:20480
	s_barrier
	s_waitcnt lgkmcnt(0)
	v_mfma_f32_32x32x16_bf16 v[66:81], v[130:133], v[176:179], v[66:81]
	v_mfma_f32_32x32x16_bf16 v[34:49], v[146:149], v[176:179], v[34:49]
	v_mfma_f32_32x32x16_bf16 v[66:81], v[134:137], v[180:183], v[66:81]
	v_mfma_f32_32x32x16_bf16 v[34:49], v[150:153], v[180:183], v[34:49]
	v_mfma_f32_32x32x16_bf16 v[66:81], v[138:141], v[192:195], v[66:81]
	v_mfma_f32_32x32x16_bf16 v[34:49], v[168:171], v[192:195], v[34:49]
	v_mfma_f32_32x32x16_bf16 v[66:81], v[142:145], v[196:199], v[66:81]
	v_mfma_f32_32x32x16_bf16 v[34:49], v[172:175], v[196:199], v[34:49]
	v_mfma_f32_32x32x16_bf16 v[18:33], v[130:133], v[200:203], v[18:33]
	v_mfma_f32_32x32x16_bf16 v[2:17], v[146:149], v[200:203], v[2:17]
	v_mfma_f32_32x32x16_bf16 v[18:33], v[134:137], v[228:231], v[18:33]
	v_mfma_f32_32x32x16_bf16 v[2:17], v[150:153], v[228:231], v[2:17]
	v_mfma_f32_32x32x16_bf16 v[18:33], v[138:141], v[232:235], v[18:33]
	v_mfma_f32_32x32x16_bf16 v[2:17], v[168:171], v[232:235], v[2:17]
	v_mfma_f32_32x32x16_bf16 v[18:33], v[142:145], v[236:239], v[18:33]
	v_mfma_f32_32x32x16_bf16 v[2:17], v[172:175], v[236:239], v[2:17]
	s_barrier
	s_cmp_eq_u32 s101, 0
	s_cbranch_scc0 .Lg8_ib_p1
	s_barrier
